# placement: the four GEMM K-loop heads aligned to 64 bytes (otherwise v64)
# speedup vs baseline: 1.0041x; 1.0006x over previous
; #define PG8_STAGE(bufoff, gbase, voff) do { _Pragma("unroll") for (int _i = 0; _i < 2; ++_i) \
;         __builtin_amdgcn_global_load_lds((const unsigned*)((const char*)(gbase) + (voff)[_i]), (PG8_LAS unsigned*)(lds + (bufoff) + ldsw + _i * 8192), 16, 0, 0); } while (0)
; #define PG8_STAGEA(bufoff, gbase, voff) do { _Pragma("unroll") for (int _i = 0; _i < 2; ++_i) \
;         __builtin_amdgcn_global_load_lds((const unsigned*)((const char*)(gbase) + (voff)[_i]), (PG8_LAS unsigned*)(lds + (bufoff) + ldsw + _i * 8192), 16, 0, A_AUX); } while (0)
; #define PG8_LDA(dst, b, h) do { _Pragma("unroll") for (int m = 0; m < 4; ++m) _Pragma("unroll") for (int k = 0; k < 2; ++k) dst[m][k] = *(const PG8_LAS bf16x8*)(lds + PG8_SA(b, h) + aoff + m * 2048 + k * 1024); } while (0)
; #define PG8_LDB(dst, b, h) do { _Pragma("unroll") for (int n = 0; n < 2; ++n) _Pragma("unroll") for (int k = 0; k < 2; ++k) dst[n][k] = *(const PG8_LAS bf16x8*)(lds + PG8_SB(b, h) + boff + n * 2048 + k * 1024); } while (0)
; #define PG8_WAIT_V(n) asm volatile("s_waitcnt vmcnt(" #n ")" ::: "memory")
; #define PG8_WAIT_L(n) asm volatile("s_waitcnt lgkmcnt(" #n ")" ::: "memory")
; #define PG8_BAR __builtin_amdgcn_s_barrier()
;     ...
;         const bool has_next = S.next(ui + 1, nxt);
;         const char* nA = has_next ? (const char*)g.A + (size_t)nxt.pm * tstep : cA; const char* nB = has_next ? (const char*)g.Bt + (size_t)nxt.pn * tstep : cB;
;         for (int t = 0; t < nt; t += 2) {
;             const bool last = (t == nt - 2);
;             const char* a1 = cA + (size_t)(t + 1) * kstep;
;             const char* a2 = last ? nA : cA + (size_t)(t + 2) * kstep; const char* b2 = last ? nB : cB + (size_t)(t + 2) * kstep;
;             const char* a3 = a2 + kstep; const char* b3 = b2 + kstep;
;             if (last && has_next) S.a_ready(nxt);
;             if constexpr (SP2) {
;             PG8_LDB(B0, 0, 0); PG8_LDB(B1, 0, 1); PG8_SCHED; PG8_LDA(At, 0, 0); PG8_STAGEA(PG8_SA(1, 1), a1 + hstep, voffA);
;             PG8_WAIT_V(8); PG8_WAIT_L(0); PG8_BAR; PG8_MMA(0, 0, At, B0); PG8_MMA(0, 1, At, B1); PG8_BAR; PG8_SCHED;
;             PG8_LDA(At, 0, 1); PG8_STAGE(PG8_SB(0, 0), b2, voffB); PG8_STAGE(PG8_SB(0, 1), b2 + hstep, voffB); PG8_STAGEA(PG8_SA(0, 0), a2, voffA);
;             PG8_WAIT_V(8); PG8_WAIT_L(0); PG8_BAR; PG8_MMA(1, 0, At, B0); PG8_MMA(1, 1, At, B1); PG8_BAR; PG8_SCHED;
.LBB0_185:
	s_ashr_i32 s53, s52, 31
	s_lshl_b64 s[16:17], s[52:53], 19
	s_add_u32 s54, s97, s16
	s_addc_u32 s55, s29, s17
	s_and_b64 s[16:17], s[38:39], exec
	s_cselect_b32 s16, s55, s1
	s_cselect_b32 s17, s54, s0
	s_ashr_i32 s51, s50, 31
	s_lshl_b64 s[42:43], s[50:51], 19
	v_readlane_b32 s51, v246, 9
	s_add_u32 s56, s51, s42
	v_readlane_b32 s42, v246, 6
	s_addc_u32 s57, s42, s43
	s_and_b64 s[42:43], s[38:39], exec
	s_cselect_b32 s51, s57, s41
	s_cselect_b32 s53, s56, s40
	s_add_u32 s0, s0, 0x40080
	s_addc_u32 s1, s1, 0
	s_add_u32 s58, s40, 0x100
	s_addc_u32 s59, s41, 0
	s_mov_b32 vcc_lo, -2
	s_add_u32 s40, s0, 0xfffc0080
	s_addc_u32 s41, s1, -1
	s_add_i32 s70, 0, 0x10000
	s_cmp_eq_u32 vcc_lo, 12
	s_cselect_b32 s43, s16, s41
	s_cselect_b32 s42, s17, s40
	s_cselect_b32 s41, s51, s59
	s_cselect_b32 s40, s53, s58
	s_add_i32 vcc_hi, 0, 0x14000
	v_add_u32_e32 v94, s70, v201
	v_add_u32_e32 v158, vcc_hi, v201
	ds_read_b128 v[74:77], v94
	ds_read_b128 v[78:81], v94 offset:1024
	ds_read_b128 v[90:93], v94 offset:2048
	ds_read_b128 v[94:97], v94 offset:3072
	ds_read_b128 v[146:149], v158
	ds_read_b128 v[150:153], v158 offset:1024
	ds_read_b128 v[154:157], v158 offset:2048
	ds_read_b128 v[158:161], v158 offset:3072
	v_lshl_add_u64 v[190:191], s[0:1], 0, v[182:183]
	s_add_i32 m0, s61, 0xc000
	ds_read_b128 v[186:189], v203
	ds_read_b128 v[208:211], v203 offset:1024
	ds_read_b128 v[212:215], v203 offset:2048
	ds_read_b128 v[216:219], v203 offset:3072
	ds_read_b128 v[220:223], v203 offset:4096
	ds_read_b128 v[224:227], v203 offset:5120
	ds_read_b128 v[228:231], v203 offset:6144
	ds_read_b128 v[232:235], v203 offset:7168
	global_load_lds_dwordx4 v[190:191], off
	v_lshl_add_u64 v[190:191], s[0:1], 0, v[184:185]
	s_add_i32 m0, s61, 0xe000
	s_nop 0
	global_load_lds_dwordx4 v[190:191], off
	s_waitcnt vmcnt(8)
	s_waitcnt lgkmcnt(0)
	s_barrier
	s_setprio 1
	s_waitcnt lgkmcnt(0)
	v_mfma_f32_16x16x32_bf16 v[142:145], v[74:77], v[186:189], 0
	v_mfma_f32_16x16x32_bf16 v[138:141], v[90:93], v[186:189], 0
	v_mfma_f32_16x16x32_bf16 v[126:129], v[74:77], v[212:215], 0
	v_mfma_f32_16x16x32_bf16 v[122:125], v[90:93], v[212:215], 0
	v_mfma_f32_16x16x32_bf16 v[110:113], v[74:77], v[220:223], 0
	v_mfma_f32_16x16x32_bf16 v[106:109], v[90:93], v[220:223], 0
	v_mfma_f32_16x16x32_bf16 v[86:89], v[74:77], v[228:231], 0
	v_mfma_f32_16x16x32_bf16 v[82:85], v[90:93], v[228:231], 0
	v_mfma_f32_16x16x32_bf16 v[142:145], v[78:81], v[208:211], v[142:145]
	v_mfma_f32_16x16x32_bf16 v[138:141], v[94:97], v[208:211], v[138:141]
	v_mfma_f32_16x16x32_bf16 v[126:129], v[78:81], v[216:219], v[126:129]
	v_mfma_f32_16x16x32_bf16 v[122:125], v[94:97], v[216:219], v[122:125]
	v_mfma_f32_16x16x32_bf16 v[110:113], v[78:81], v[224:227], v[110:113]
	v_mfma_f32_16x16x32_bf16 v[106:109], v[94:97], v[224:227], v[106:109]
	v_mfma_f32_16x16x32_bf16 v[86:89], v[78:81], v[232:235], v[86:89]
	v_mfma_f32_16x16x32_bf16 v[82:85], v[94:97], v[232:235], v[82:85]
	s_setprio 0
	s_setprio 1
	v_mfma_f32_16x16x32_bf16 v[134:137], v[146:149], v[186:189], 0
	v_mfma_f32_16x16x32_bf16 v[130:133], v[154:157], v[186:189], 0
	v_mfma_f32_16x16x32_bf16 v[118:121], v[146:149], v[212:215], 0
	v_mfma_f32_16x16x32_bf16 v[114:117], v[154:157], v[212:215], 0
	v_mfma_f32_16x16x32_bf16 v[102:105], v[146:149], v[220:223], 0
	v_mfma_f32_16x16x32_bf16 v[98:101], v[154:157], v[220:223], 0
	v_mfma_f32_16x16x32_bf16 v[70:73], v[146:149], v[228:231], 0
	v_mfma_f32_16x16x32_bf16 v[66:69], v[154:157], v[228:231], 0
	v_mfma_f32_16x16x32_bf16 v[134:137], v[150:153], v[208:211], v[134:137]
	v_mfma_f32_16x16x32_bf16 v[130:133], v[158:161], v[208:211], v[130:133]
	v_mfma_f32_16x16x32_bf16 v[118:121], v[150:153], v[216:219], v[118:121]
	v_mfma_f32_16x16x32_bf16 v[114:117], v[158:161], v[216:219], v[114:117]
	v_mfma_f32_16x16x32_bf16 v[102:105], v[150:153], v[224:227], v[102:105]
	v_mfma_f32_16x16x32_bf16 v[98:101], v[158:161], v[224:227], v[98:101]
	v_mfma_f32_16x16x32_bf16 v[70:73], v[150:153], v[232:235], v[70:73]
	v_mfma_f32_16x16x32_bf16 v[66:69], v[158:161], v[232:235], v[66:69]
	s_setprio 0
	s_barrier
	s_add_i32 s70, s70, s60
	v_lshl_add_u64 v[190:191], s[40:41], 0, v[0:1]
	s_mov_b32 m0, s70
	ds_read_b128 v[186:189], v203 offset:16384
	ds_read_b128 v[208:211], v203 offset:17408
	ds_read_b128 v[212:215], v203 offset:18432
	ds_read_b128 v[216:219], v203 offset:19456
	ds_read_b128 v[220:223], v203 offset:20480
	ds_read_b128 v[224:227], v203 offset:21504
	ds_read_b128 v[228:231], v203 offset:22528
	ds_read_b128 v[232:235], v203 offset:23552
	global_load_lds_dwordx4 v[190:191], off
	s_add_i32 m0, s70, 0x2000
	s_add_u32 s70, s40, 0x40000
	v_lshl_add_u64 v[236:237], s[40:41], 0, v[174:175]
	s_addc_u32 s71, s41, 0
	s_add_i32 vcc_hi, vcc_hi, s60
	global_load_lds_dwordx4 v[236:237], off
	v_lshl_add_u64 v[238:239], s[70:71], 0, v[0:1]
	s_mov_b32 m0, vcc_hi
	v_lshl_add_u64 v[240:241], s[42:43], 0, v[176:177]
	global_load_lds_dwordx4 v[238:239], off
	v_lshl_add_u64 v[238:239], s[70:71], 0, v[174:175]
	s_add_i32 m0, vcc_hi, 0x2000
	s_nop 0
	global_load_lds_dwordx4 v[238:239], off
	v_lshl_add_u64 v[238:239], s[42:43], 0, v[178:179]
	s_mov_b32 m0, s61
	s_nop 0
	global_load_lds_dwordx4 v[238:239], off
	s_mov_b32 m0, s62
	s_nop 0
	global_load_lds_dwordx4 v[240:241], off
	s_waitcnt vmcnt(8)
	s_waitcnt lgkmcnt(0)
	s_barrier
; #define PG8_STAGEA(bufoff, gbase, voff) do { _Pragma("unroll") for (int _i = 0; _i < 2; ++_i) \
;         __builtin_amdgcn_global_load_lds((const unsigned*)((const char*)(gbase) + (voff)[_i]), (PG8_LAS unsigned*)(lds + (bufoff) + ldsw + _i * 8192), 16, 0, A_AUX); } while (0)
; #define PG8_LDA(dst, b, h) do { _Pragma("unroll") for (int m = 0; m < 4; ++m) _Pragma("unroll") for (int k = 0; k < 2; ++k) dst[m][k] = *(const PG8_LAS bf16x8*)(lds + PG8_SA(b, h) + aoff + m * 2048 + k * 1024); } while (0)
; #define PG8_LDB(dst, b, h) do { _Pragma("unroll") for (int n = 0; n < 2; ++n) _Pragma("unroll") for (int k = 0; k < 2; ++k) dst[n][k] = *(const PG8_LAS bf16x8*)(lds + PG8_SB(b, h) + boff + n * 2048 + k * 1024); } while (0)
; #define PG8_MMA(ai, bj, At, Bt) do { __builtin_amdgcn_s_setprio(1); _Pragma("unroll") for (int m = 0; m < 4; ++m) _Pragma("unroll") for (int n = 0; n < 2; ++n) _Pragma("unroll") for (int k = 0; k < 2; ++k) \
;         acc[ai][bj][m][n] = __builtin_amdgcn_mfma_f32_16x16x32_bf16(Bt[n][k], At[m][k], acc[ai][bj][m][n], 0, 0, 0); __builtin_amdgcn_s_setprio(0); } while (0)
; #define PG8_WAIT_V(n) asm volatile("s_waitcnt vmcnt(" #n ")" ::: "memory")
; #define PG8_WAIT_L(n) asm volatile("s_waitcnt lgkmcnt(" #n ")" ::: "memory")
; #define PG8_BAR __builtin_amdgcn_s_barrier()
; #define PG8_SCHED __builtin_amdgcn_sched_barrier(0)
;     ...
;             PG8_WAIT_V(8); PG8_WAIT_L(0); PG8_BAR; PG8_MMA(1, 0, At, B0); PG8_MMA(1, 1, At, B1); PG8_BAR; PG8_SCHED;
;             PG8_LDB(B0, 1, 0); PG8_LDB(B1, 1, 1); PG8_SCHED; PG8_LDA(At, 1, 0); PG8_STAGEA(PG8_SA(0, 1), a2 + hstep, voffA);
;             PG8_WAIT_V(8); PG8_WAIT_L(0); PG8_BAR; PG8_MMA(0, 0, At, B0); PG8_MMA(0, 1, At, B1); PG8_BAR; PG8_SCHED;
	s_setprio 1
	s_waitcnt lgkmcnt(0)
	v_mfma_f32_16x16x32_bf16 v[62:65], v[74:77], v[186:189], 0
	v_mfma_f32_16x16x32_bf16 v[58:61], v[90:93], v[186:189], 0
	v_mfma_f32_16x16x32_bf16 v[46:49], v[74:77], v[212:215], 0
	v_mfma_f32_16x16x32_bf16 v[42:45], v[90:93], v[212:215], 0
	v_mfma_f32_16x16x32_bf16 v[30:33], v[74:77], v[220:223], 0
	v_mfma_f32_16x16x32_bf16 v[26:29], v[90:93], v[220:223], 0
	v_mfma_f32_16x16x32_bf16 v[14:17], v[74:77], v[228:231], 0
	v_mfma_f32_16x16x32_bf16 v[10:13], v[90:93], v[228:231], 0
	v_mfma_f32_16x16x32_bf16 v[62:65], v[78:81], v[208:211], v[62:65]
	v_mfma_f32_16x16x32_bf16 v[58:61], v[94:97], v[208:211], v[58:61]
	v_mfma_f32_16x16x32_bf16 v[46:49], v[78:81], v[216:219], v[46:49]
	v_mfma_f32_16x16x32_bf16 v[42:45], v[94:97], v[216:219], v[42:45]
	v_mfma_f32_16x16x32_bf16 v[30:33], v[78:81], v[224:227], v[30:33]
	v_mfma_f32_16x16x32_bf16 v[26:29], v[94:97], v[224:227], v[26:29]
	v_mfma_f32_16x16x32_bf16 v[14:17], v[78:81], v[232:235], v[14:17]
	v_mfma_f32_16x16x32_bf16 v[10:13], v[94:97], v[232:235], v[10:13]
	s_setprio 0
	s_setprio 1
	v_mfma_f32_16x16x32_bf16 v[54:57], v[146:149], v[186:189], 0
	v_mfma_f32_16x16x32_bf16 v[50:53], v[154:157], v[186:189], 0
	v_mfma_f32_16x16x32_bf16 v[38:41], v[146:149], v[212:215], 0
	v_mfma_f32_16x16x32_bf16 v[34:37], v[154:157], v[212:215], 0
	v_mfma_f32_16x16x32_bf16 v[22:25], v[146:149], v[220:223], 0
	v_mfma_f32_16x16x32_bf16 v[18:21], v[154:157], v[220:223], 0
	v_mfma_f32_16x16x32_bf16 v[6:9], v[146:149], v[228:231], 0
	v_mfma_f32_16x16x32_bf16 v[2:5], v[154:157], v[228:231], 0
	v_mfma_f32_16x16x32_bf16 v[54:57], v[150:153], v[208:211], v[54:57]
	v_mfma_f32_16x16x32_bf16 v[50:53], v[158:161], v[208:211], v[50:53]
	v_mfma_f32_16x16x32_bf16 v[38:41], v[150:153], v[216:219], v[38:41]
	v_mfma_f32_16x16x32_bf16 v[34:37], v[158:161], v[216:219], v[34:37]
	v_mfma_f32_16x16x32_bf16 v[22:25], v[150:153], v[224:227], v[22:25]
	v_mfma_f32_16x16x32_bf16 v[18:21], v[158:161], v[224:227], v[18:21]
	v_mfma_f32_16x16x32_bf16 v[6:9], v[150:153], v[232:235], v[6:9]
	v_mfma_f32_16x16x32_bf16 v[2:5], v[158:161], v[232:235], v[2:5]
	s_setprio 0
	s_barrier
	s_add_i32 s70, 0, 0x18000
	s_add_i32 s71, 0, 0x1c000
	v_add_u32_e32 v94, s70, v201
	v_add_u32_e32 v158, s71, v201
	ds_read_b128 v[74:77], v94
	ds_read_b128 v[78:81], v94 offset:1024
	ds_read_b128 v[90:93], v94 offset:2048
	ds_read_b128 v[94:97], v94 offset:3072
	ds_read_b128 v[146:149], v158
	ds_read_b128 v[150:153], v158 offset:1024
	ds_read_b128 v[154:157], v158 offset:2048
	ds_read_b128 v[158:161], v158 offset:3072
	s_add_u32 s42, s42, 0x40000
	s_addc_u32 s43, s43, 0
	s_mov_b32 m0, s63
	v_lshl_add_u64 v[242:243], s[42:43], 0, v[178:179]
	ds_read_b128 v[186:189], v203 offset:32768
	ds_read_b128 v[208:211], v203 offset:33792
	ds_read_b128 v[212:215], v203 offset:34816
	ds_read_b128 v[216:219], v203 offset:35840
	ds_read_b128 v[220:223], v203 offset:36864
	ds_read_b128 v[224:227], v203 offset:37888
	ds_read_b128 v[228:231], v203 offset:38912
	ds_read_b128 v[232:235], v203 offset:39936
	global_load_lds_dwordx4 v[242:243], off
	v_lshl_add_u64 v[242:243], s[42:43], 0, v[176:177]
	s_mov_b32 m0, s64
	s_nop 0
	global_load_lds_dwordx4 v[242:243], off
	s_waitcnt vmcnt(8)
	s_waitcnt lgkmcnt(0)
	s_barrier
	s_setprio 1
	s_waitcnt lgkmcnt(0)
	v_mfma_f32_16x16x32_bf16 v[142:145], v[74:77], v[186:189], v[142:145]
	v_mfma_f32_16x16x32_bf16 v[138:141], v[90:93], v[186:189], v[138:141]
	v_mfma_f32_16x16x32_bf16 v[126:129], v[74:77], v[212:215], v[126:129]
	v_mfma_f32_16x16x32_bf16 v[122:125], v[90:93], v[212:215], v[122:125]
	v_mfma_f32_16x16x32_bf16 v[110:113], v[74:77], v[220:223], v[110:113]
	v_mfma_f32_16x16x32_bf16 v[106:109], v[90:93], v[220:223], v[106:109]
	v_mfma_f32_16x16x32_bf16 v[86:89], v[74:77], v[228:231], v[86:89]
	v_mfma_f32_16x16x32_bf16 v[82:85], v[90:93], v[228:231], v[82:85]
	v_mfma_f32_16x16x32_bf16 v[142:145], v[78:81], v[208:211], v[142:145]
	v_mfma_f32_16x16x32_bf16 v[138:141], v[94:97], v[208:211], v[138:141]
	v_mfma_f32_16x16x32_bf16 v[126:129], v[78:81], v[216:219], v[126:129]
	v_mfma_f32_16x16x32_bf16 v[122:125], v[94:97], v[216:219], v[122:125]
	v_mfma_f32_16x16x32_bf16 v[110:113], v[78:81], v[224:227], v[110:113]
	v_mfma_f32_16x16x32_bf16 v[106:109], v[94:97], v[224:227], v[106:109]
	v_mfma_f32_16x16x32_bf16 v[86:89], v[78:81], v[232:235], v[86:89]
	v_mfma_f32_16x16x32_bf16 v[82:85], v[94:97], v[232:235], v[82:85]
	s_setprio 0
	s_setprio 1
	v_mfma_f32_16x16x32_bf16 v[134:137], v[146:149], v[186:189], v[134:137]
	v_mfma_f32_16x16x32_bf16 v[130:133], v[154:157], v[186:189], v[130:133]
	v_mfma_f32_16x16x32_bf16 v[118:121], v[146:149], v[212:215], v[118:121]
	v_mfma_f32_16x16x32_bf16 v[114:117], v[154:157], v[212:215], v[114:117]
	v_mfma_f32_16x16x32_bf16 v[102:105], v[146:149], v[220:223], v[102:105]
	v_mfma_f32_16x16x32_bf16 v[98:101], v[154:157], v[220:223], v[98:101]
	v_mfma_f32_16x16x32_bf16 v[70:73], v[146:149], v[228:231], v[70:73]
	v_mfma_f32_16x16x32_bf16 v[66:69], v[154:157], v[228:231], v[66:69]
	v_mfma_f32_16x16x32_bf16 v[134:137], v[150:153], v[208:211], v[134:137]
	v_mfma_f32_16x16x32_bf16 v[130:133], v[158:161], v[208:211], v[130:133]
	v_mfma_f32_16x16x32_bf16 v[118:121], v[150:153], v[216:219], v[118:121]
	v_mfma_f32_16x16x32_bf16 v[114:117], v[158:161], v[216:219], v[114:117]
	v_mfma_f32_16x16x32_bf16 v[102:105], v[150:153], v[224:227], v[102:105]
	v_mfma_f32_16x16x32_bf16 v[98:101], v[158:161], v[224:227], v[98:101]
	v_mfma_f32_16x16x32_bf16 v[70:73], v[150:153], v[232:235], v[70:73]
	v_mfma_f32_16x16x32_bf16 v[66:69], v[158:161], v[232:235], v[66:69]
	s_setprio 0
	s_barrier
; #define PG8_STAGE(bufoff, gbase, voff) do { _Pragma("unroll") for (int _i = 0; _i < 2; ++_i) \
;         __builtin_amdgcn_global_load_lds((const unsigned*)((const char*)(gbase) + (voff)[_i]), (PG8_LAS unsigned*)(lds + (bufoff) + ldsw + _i * 8192), 16, 0, 0); } while (0)
; #define PG8_STAGEA(bufoff, gbase, voff) do { _Pragma("unroll") for (int _i = 0; _i < 2; ++_i) \
;         __builtin_amdgcn_global_load_lds((const unsigned*)((const char*)(gbase) + (voff)[_i]), (PG8_LAS unsigned*)(lds + (bufoff) + ldsw + _i * 8192), 16, 0, A_AUX); } while (0)
; #define PG8_LDA(dst, b, h) do { _Pragma("unroll") for (int m = 0; m < 4; ++m) _Pragma("unroll") for (int k = 0; k < 2; ++k) dst[m][k] = *(const PG8_LAS bf16x8*)(lds + PG8_SA(b, h) + aoff + m * 2048 + k * 1024); } while (0)
; #define PG8_MMA(ai, bj, At, Bt) do { __builtin_amdgcn_s_setprio(1); _Pragma("unroll") for (int m = 0; m < 4; ++m) _Pragma("unroll") for (int n = 0; n < 2; ++n) _Pragma("unroll") for (int k = 0; k < 2; ++k) \
;         acc[ai][bj][m][n] = __builtin_amdgcn_mfma_f32_16x16x32_bf16(Bt[n][k], At[m][k], acc[ai][bj][m][n], 0, 0, 0); __builtin_amdgcn_s_setprio(0); } while (0)
; #define PG8_WAIT_V(n) asm volatile("s_waitcnt vmcnt(" #n ")" ::: "memory")
; #define PG8_WAIT_L(n) asm volatile("s_waitcnt lgkmcnt(" #n ")" ::: "memory")
; #define PG8_BAR __builtin_amdgcn_s_barrier()
; #define PG8_SCHED __builtin_amdgcn_sched_barrier(0)
;     ...
;             PG8_LDA(At, 1, 1); PG8_STAGE(PG8_SB(1, 0), b3, voffB); PG8_STAGE(PG8_SB(1, 1), b3 + hstep, voffB); PG8_STAGEA(PG8_SA(1, 0), a3, voffA);
;             PG8_WAIT_V(8); PG8_WAIT_L(0); PG8_BAR; PG8_MMA(1, 0, At, B0); PG8_MMA(1, 1, At, B1); PG8_BAR; PG8_SCHED;
	s_add_i32 s42, s70, s60
	v_lshl_add_u64 v[190:191], v[190:191], 0, s[8:9]
	s_mov_b32 m0, s42
	ds_read_b128 v[186:189], v203 offset:49152
	ds_read_b128 v[208:211], v203 offset:50176
	ds_read_b128 v[212:215], v203 offset:51200
	ds_read_b128 v[216:219], v203 offset:52224
	ds_read_b128 v[220:223], v203 offset:53248
	ds_read_b128 v[224:227], v203 offset:54272
	ds_read_b128 v[228:231], v203 offset:55296
	ds_read_b128 v[232:235], v203 offset:56320
	global_load_lds_dwordx4 v[190:191], off
	s_add_i32 m0, s42, 0x2000
	s_add_u32 s40, s40, 0x40080
	v_lshl_add_u64 v[190:191], v[236:237], 0, s[8:9]
	s_addc_u32 s41, s41, 0
	s_add_i32 s42, s71, s60
	global_load_lds_dwordx4 v[190:191], off
	v_lshl_add_u64 v[190:191], s[40:41], 0, v[0:1]
	s_mov_b32 m0, s42
	s_nop 0
	global_load_lds_dwordx4 v[190:191], off
	v_lshl_add_u64 v[190:191], s[40:41], 0, v[174:175]
	s_add_i32 m0, s42, 0x2000
	s_nop 0
	global_load_lds_dwordx4 v[190:191], off
	v_lshl_add_u64 v[190:191], v[238:239], 0, s[8:9]
	s_mov_b32 m0, s72
	s_nop 0
	global_load_lds_dwordx4 v[190:191], off
	v_lshl_add_u64 v[190:191], v[240:241], 0, s[8:9]
	s_mov_b32 m0, s73
	s_nop 0
	global_load_lds_dwordx4 v[190:191], off
	s_waitcnt vmcnt(8)
	s_waitcnt lgkmcnt(0)
	s_barrier
	s_setprio 1
	s_waitcnt lgkmcnt(0)
	v_mfma_f32_16x16x32_bf16 v[62:65], v[74:77], v[186:189], v[62:65]
	v_mfma_f32_16x16x32_bf16 v[58:61], v[90:93], v[186:189], v[58:61]
	v_mfma_f32_16x16x32_bf16 v[46:49], v[74:77], v[212:215], v[46:49]
	v_mfma_f32_16x16x32_bf16 v[42:45], v[90:93], v[212:215], v[42:45]
	v_mfma_f32_16x16x32_bf16 v[30:33], v[74:77], v[220:223], v[30:33]
	v_mfma_f32_16x16x32_bf16 v[26:29], v[90:93], v[220:223], v[26:29]
	v_mfma_f32_16x16x32_bf16 v[14:17], v[74:77], v[228:231], v[14:17]
	v_mfma_f32_16x16x32_bf16 v[10:13], v[90:93], v[228:231], v[10:13]
	v_mfma_f32_16x16x32_bf16 v[62:65], v[78:81], v[208:211], v[62:65]
	v_mfma_f32_16x16x32_bf16 v[58:61], v[94:97], v[208:211], v[58:61]
	v_mfma_f32_16x16x32_bf16 v[46:49], v[78:81], v[216:219], v[46:49]
	v_mfma_f32_16x16x32_bf16 v[42:45], v[94:97], v[216:219], v[42:45]
	v_mfma_f32_16x16x32_bf16 v[30:33], v[78:81], v[224:227], v[30:33]
	v_mfma_f32_16x16x32_bf16 v[26:29], v[94:97], v[224:227], v[26:29]
	v_mfma_f32_16x16x32_bf16 v[14:17], v[78:81], v[232:235], v[14:17]
	v_mfma_f32_16x16x32_bf16 v[10:13], v[94:97], v[232:235], v[10:13]
	s_setprio 0
	s_setprio 1
	v_mfma_f32_16x16x32_bf16 v[54:57], v[146:149], v[186:189], v[54:57]
	v_mfma_f32_16x16x32_bf16 v[50:53], v[154:157], v[186:189], v[50:53]
	v_mfma_f32_16x16x32_bf16 v[38:41], v[146:149], v[212:215], v[38:41]
	v_mfma_f32_16x16x32_bf16 v[34:37], v[154:157], v[212:215], v[34:37]
	v_mfma_f32_16x16x32_bf16 v[22:25], v[146:149], v[220:223], v[22:25]
	v_mfma_f32_16x16x32_bf16 v[18:21], v[154:157], v[220:223], v[18:21]
	v_mfma_f32_16x16x32_bf16 v[6:9], v[146:149], v[228:231], v[6:9]
	v_mfma_f32_16x16x32_bf16 v[2:5], v[154:157], v[228:231], v[2:5]
	v_mfma_f32_16x16x32_bf16 v[54:57], v[150:153], v[208:211], v[54:57]
	v_mfma_f32_16x16x32_bf16 v[50:53], v[158:161], v[208:211], v[50:53]
	v_mfma_f32_16x16x32_bf16 v[38:41], v[150:153], v[216:219], v[38:41]
	v_mfma_f32_16x16x32_bf16 v[34:37], v[158:161], v[216:219], v[34:37]
	v_mfma_f32_16x16x32_bf16 v[22:25], v[150:153], v[224:227], v[22:25]
	v_mfma_f32_16x16x32_bf16 v[18:21], v[158:161], v[224:227], v[18:21]
	v_mfma_f32_16x16x32_bf16 v[6:9], v[150:153], v[232:235], v[6:9]
	v_mfma_f32_16x16x32_bf16 v[2:5], v[158:161], v[232:235], v[2:5]
	s_setprio 0
	s_barrier
	s_add_i32 vcc_lo, vcc_lo, 2
	s_add_u32 s0, s0, 0x100
	s_addc_u32 s1, s1, 0
	s_add_u32 s58, s58, 0x100
	s_addc_u32 s59, s59, 0
	.p2align 6

; #define PG8_STAGE(bufoff, gbase, voff) do { _Pragma("unroll") for (int _i = 0; _i < 2; ++_i) \
;         __builtin_amdgcn_global_load_lds((const unsigned*)((const char*)(gbase) + (voff)[_i]), (PG8_LAS unsigned*)(lds + (bufoff) + ldsw + _i * 8192), 16, 0, 0); } while (0)
; #define PG8_STAGEA(bufoff, gbase, voff) do { _Pragma("unroll") for (int _i = 0; _i < 2; ++_i) \
;         __builtin_amdgcn_global_load_lds((const unsigned*)((const char*)(gbase) + (voff)[_i]), (PG8_LAS unsigned*)(lds + (bufoff) + ldsw + _i * 8192), 16, 0, A_AUX); } while (0)
; #define PG8_LDA(dst, b, h) do { _Pragma("unroll") for (int m = 0; m < 4; ++m) _Pragma("unroll") for (int k = 0; k < 2; ++k) dst[m][k] = *(const PG8_LAS bf16x8*)(lds + PG8_SA(b, h) + aoff + m * 2048 + k * 1024); } while (0)
; #define PG8_LDB(dst, b, h) do { _Pragma("unroll") for (int n = 0; n < 2; ++n) _Pragma("unroll") for (int k = 0; k < 2; ++k) dst[n][k] = *(const PG8_LAS bf16x8*)(lds + PG8_SB(b, h) + boff + n * 2048 + k * 1024); } while (0)
; #define PG8_WAIT_V(n) asm volatile("s_waitcnt vmcnt(" #n ")" ::: "memory")
; #define PG8_WAIT_L(n) asm volatile("s_waitcnt lgkmcnt(" #n ")" ::: "memory")
; #define PG8_BAR __builtin_amdgcn_s_barrier()
;     ...
;         const bool has_next = S.next(ui + 1, nxt);
;         const char* nA = has_next ? (const char*)g.A + (size_t)nxt.pm * tstep : cA; const char* nB = has_next ? (const char*)g.Bt + (size_t)nxt.pn * tstep : cB;
;         for (int t = 0; t < nt; t += 2) {
;             const bool last = (t == nt - 2);
;             const char* a1 = cA + (size_t)(t + 1) * kstep;
;             const char* a2 = last ? nA : cA + (size_t)(t + 2) * kstep; const char* b2 = last ? nB : cB + (size_t)(t + 2) * kstep;
;             const char* a3 = a2 + kstep; const char* b3 = b2 + kstep;
;             if (last && has_next) S.a_ready(nxt);
;             if constexpr (SP2) {
;             PG8_LDB(B0, 0, 0); PG8_LDB(B1, 0, 1); PG8_SCHED; PG8_LDA(At, 0, 0); PG8_STAGEA(PG8_SA(1, 1), a1 + hstep, voffA);
;             PG8_WAIT_V(8); PG8_WAIT_L(0); PG8_BAR; PG8_MMA(0, 0, At, B0); PG8_MMA(0, 1, At, B1); PG8_BAR; PG8_SCHED;
;             PG8_LDA(At, 0, 1); PG8_STAGE(PG8_SB(0, 0), b2, voffB); PG8_STAGE(PG8_SB(0, 1), b2 + hstep, voffB); PG8_STAGEA(PG8_SA(0, 0), a2, voffA);
;             PG8_WAIT_V(8); PG8_WAIT_L(0); PG8_BAR; PG8_MMA(1, 0, At, B0); PG8_MMA(1, 1, At, B1); PG8_BAR; PG8_SCHED;
.LBB0_442:
	s_ashr_i32 s43, s42, 31
	s_lshl_b64 s[16:17], s[42:43], 19
	s_add_u32 s44, s24, s16
	s_addc_u32 s45, s25, s17
	s_and_b64 s[16:17], s[38:39], exec
	s_cselect_b32 s16, s45, s49
	s_cselect_b32 s17, s44, s48
	s_ashr_i32 s41, s40, 31
	s_lshl_b64 s[46:47], s[40:41], 19
	s_add_u32 s46, s23, s46
	s_addc_u32 s47, s54, s47
	s_and_b64 s[52:53], s[38:39], exec
	s_cselect_b32 s41, s47, s51
	s_cselect_b32 s43, s46, s50
	s_add_u32 s48, s48, 0x40080
	s_addc_u32 s49, s49, 0
	s_add_u32 s65, s50, 0x100
	s_addc_u32 s72, s51, 0
	s_mov_b32 s73, -2
	s_add_u32 s50, s48, 0xfffc0080
	s_addc_u32 s51, s49, -1
	s_add_i32 s70, 0, 0x10000
	s_cmp_eq_u32 s73, 12
	s_cselect_b32 s53, s16, s51
	s_cselect_b32 s52, s17, s50
	v_add_u32_e32 v140, s70, v143
	s_cselect_b32 s51, s41, s72
	s_cselect_b32 s50, s43, s65
	s_add_i32 s76, 0, 0x14000
	ds_read_b128 v[146:149], v140
	ds_read_b128 v[150:153], v140 offset:1024
	ds_read_b128 v[154:157], v140 offset:2048
	ds_read_b128 v[158:161], v140 offset:3072
	v_add_u32_e32 v140, s76, v143
	ds_read_b128 v[174:177], v140
	ds_read_b128 v[178:181], v140 offset:1024
	ds_read_b128 v[182:185], v140 offset:2048
	ds_read_b128 v[186:189], v140 offset:3072
	v_lshl_add_u64 v[140:141], s[48:49], 0, v[136:137]
	s_add_i32 m0, s56, 0xc000
	ds_read_b128 v[200:203], v145
	ds_read_b128 v[208:211], v145 offset:1024
	ds_read_b128 v[212:215], v145 offset:2048
	ds_read_b128 v[216:219], v145 offset:3072
	ds_read_b128 v[220:223], v145 offset:4096
	ds_read_b128 v[224:227], v145 offset:5120
	ds_read_b128 v[228:231], v145 offset:6144
	ds_read_b128 v[232:235], v145 offset:7168
	global_load_lds_dwordx4 v[140:141], off
	v_lshl_add_u64 v[140:141], s[48:49], 0, v[138:139]
	s_add_i32 m0, s56, 0xe000
	s_nop 0
	global_load_lds_dwordx4 v[140:141], off
	s_waitcnt vmcnt(8)
	s_waitcnt lgkmcnt(0)
	s_barrier
	s_setprio 1
	s_waitcnt lgkmcnt(0)
	v_mfma_f32_16x16x32_bf16 v[126:129], v[146:149], v[200:203], 0
	v_mfma_f32_16x16x32_bf16 v[122:125], v[154:157], v[200:203], 0
	v_mfma_f32_16x16x32_bf16 v[114:117], v[146:149], v[212:215], 0
	v_mfma_f32_16x16x32_bf16 v[106:109], v[154:157], v[212:215], 0
	v_mfma_f32_16x16x32_bf16 v[98:101], v[146:149], v[220:223], 0
	v_mfma_f32_16x16x32_bf16 v[90:93], v[154:157], v[220:223], 0
	v_mfma_f32_16x16x32_bf16 v[82:85], v[146:149], v[228:231], 0
	v_mfma_f32_16x16x32_bf16 v[74:77], v[154:157], v[228:231], 0
	v_mfma_f32_16x16x32_bf16 v[126:129], v[150:153], v[208:211], v[126:129]
	v_mfma_f32_16x16x32_bf16 v[122:125], v[158:161], v[208:211], v[122:125]
	v_mfma_f32_16x16x32_bf16 v[114:117], v[150:153], v[216:219], v[114:117]
	v_mfma_f32_16x16x32_bf16 v[106:109], v[158:161], v[216:219], v[106:109]
	v_mfma_f32_16x16x32_bf16 v[98:101], v[150:153], v[224:227], v[98:101]
	v_mfma_f32_16x16x32_bf16 v[90:93], v[158:161], v[224:227], v[90:93]
	v_mfma_f32_16x16x32_bf16 v[82:85], v[150:153], v[232:235], v[82:85]
	v_mfma_f32_16x16x32_bf16 v[74:77], v[158:161], v[232:235], v[74:77]
	s_setprio 0
	s_setprio 1
	v_mfma_f32_16x16x32_bf16 v[118:121], v[174:177], v[200:203], 0
	v_mfma_f32_16x16x32_bf16 v[110:113], v[182:185], v[200:203], 0
	v_mfma_f32_16x16x32_bf16 v[102:105], v[174:177], v[212:215], 0
	v_mfma_f32_16x16x32_bf16 v[94:97], v[182:185], v[212:215], 0
	v_mfma_f32_16x16x32_bf16 v[86:89], v[174:177], v[220:223], 0
	v_mfma_f32_16x16x32_bf16 v[78:81], v[182:185], v[220:223], 0
	v_mfma_f32_16x16x32_bf16 v[70:73], v[174:177], v[228:231], 0
	v_mfma_f32_16x16x32_bf16 v[66:69], v[182:185], v[228:231], 0
	v_mfma_f32_16x16x32_bf16 v[118:121], v[178:181], v[208:211], v[118:121]
	v_mfma_f32_16x16x32_bf16 v[110:113], v[186:189], v[208:211], v[110:113]
	v_mfma_f32_16x16x32_bf16 v[102:105], v[178:181], v[216:219], v[102:105]
	v_mfma_f32_16x16x32_bf16 v[94:97], v[186:189], v[216:219], v[94:97]
	v_mfma_f32_16x16x32_bf16 v[86:89], v[178:181], v[224:227], v[86:89]
	v_mfma_f32_16x16x32_bf16 v[78:81], v[186:189], v[224:227], v[78:81]
	v_mfma_f32_16x16x32_bf16 v[70:73], v[178:181], v[232:235], v[70:73]
	v_mfma_f32_16x16x32_bf16 v[66:69], v[186:189], v[232:235], v[66:69]
	s_setprio 0
	s_barrier
	s_add_i32 s70, s70, s55
	v_lshl_add_u64 v[140:141], s[50:51], 0, v[0:1]
	s_mov_b32 m0, s70
	ds_read_b128 v[200:203], v145 offset:16384
	ds_read_b128 v[208:211], v145 offset:17408
	ds_read_b128 v[212:215], v145 offset:18432
	ds_read_b128 v[216:219], v145 offset:19456
	ds_read_b128 v[220:223], v145 offset:20480
	ds_read_b128 v[224:227], v145 offset:21504
	ds_read_b128 v[228:231], v145 offset:22528
	ds_read_b128 v[232:235], v145 offset:23552
	global_load_lds_dwordx4 v[140:141], off
	s_add_i32 m0, s70, 0x2000
	s_add_u32 s70, s50, 0x40000
	v_lshl_add_u64 v[190:191], s[50:51], 0, v[130:131]
	s_addc_u32 s71, s51, 0
	s_add_i32 s76, s76, s55
	global_load_lds_dwordx4 v[190:191], off
	v_lshl_add_u64 v[236:237], s[70:71], 0, v[0:1]
	s_mov_b32 m0, s76
	v_lshl_add_u64 v[238:239], s[52:53], 0, v[132:133]
	global_load_lds_dwordx4 v[236:237], off
	v_lshl_add_u64 v[236:237], s[70:71], 0, v[130:131]
	s_add_i32 m0, s76, 0x2000
	s_nop 0
	global_load_lds_dwordx4 v[236:237], off
	v_lshl_add_u64 v[236:237], s[52:53], 0, v[134:135]
	s_mov_b32 m0, s56
	s_nop 0
	global_load_lds_dwordx4 v[236:237], off
	s_mov_b32 m0, s57
	s_nop 0
	global_load_lds_dwordx4 v[238:239], off
	s_waitcnt vmcnt(8)
	s_waitcnt lgkmcnt(0)
	s_barrier
; #define PG8_STAGEA(bufoff, gbase, voff) do { _Pragma("unroll") for (int _i = 0; _i < 2; ++_i) \
;         __builtin_amdgcn_global_load_lds((const unsigned*)((const char*)(gbase) + (voff)[_i]), (PG8_LAS unsigned*)(lds + (bufoff) + ldsw + _i * 8192), 16, 0, A_AUX); } while (0)
; #define PG8_LDA(dst, b, h) do { _Pragma("unroll") for (int m = 0; m < 4; ++m) _Pragma("unroll") for (int k = 0; k < 2; ++k) dst[m][k] = *(const PG8_LAS bf16x8*)(lds + PG8_SA(b, h) + aoff + m * 2048 + k * 1024); } while (0)
; #define PG8_LDB(dst, b, h) do { _Pragma("unroll") for (int n = 0; n < 2; ++n) _Pragma("unroll") for (int k = 0; k < 2; ++k) dst[n][k] = *(const PG8_LAS bf16x8*)(lds + PG8_SB(b, h) + boff + n * 2048 + k * 1024); } while (0)
; #define PG8_MMA(ai, bj, At, Bt) do { __builtin_amdgcn_s_setprio(1); _Pragma("unroll") for (int m = 0; m < 4; ++m) _Pragma("unroll") for (int n = 0; n < 2; ++n) _Pragma("unroll") for (int k = 0; k < 2; ++k) \
;         acc[ai][bj][m][n] = __builtin_amdgcn_mfma_f32_16x16x32_bf16(Bt[n][k], At[m][k], acc[ai][bj][m][n], 0, 0, 0); __builtin_amdgcn_s_setprio(0); } while (0)
; #define PG8_WAIT_V(n) asm volatile("s_waitcnt vmcnt(" #n ")" ::: "memory")
; #define PG8_WAIT_L(n) asm volatile("s_waitcnt lgkmcnt(" #n ")" ::: "memory")
; #define PG8_BAR __builtin_amdgcn_s_barrier()
; #define PG8_SCHED __builtin_amdgcn_sched_barrier(0)
;     ...
;             PG8_WAIT_V(8); PG8_WAIT_L(0); PG8_BAR; PG8_MMA(1, 0, At, B0); PG8_MMA(1, 1, At, B1); PG8_BAR; PG8_SCHED;
;             PG8_LDB(B0, 1, 0); PG8_LDB(B1, 1, 1); PG8_SCHED; PG8_LDA(At, 1, 0); PG8_STAGEA(PG8_SA(0, 1), a2 + hstep, voffA);
;             PG8_WAIT_V(8); PG8_WAIT_L(0); PG8_BAR; PG8_MMA(0, 0, At, B0); PG8_MMA(0, 1, At, B1); PG8_BAR; PG8_SCHED;
	s_setprio 1
	s_waitcnt lgkmcnt(0)
	v_mfma_f32_16x16x32_bf16 v[62:65], v[146:149], v[200:203], 0
	v_mfma_f32_16x16x32_bf16 v[58:61], v[154:157], v[200:203], 0
	v_mfma_f32_16x16x32_bf16 v[50:53], v[146:149], v[212:215], 0
	v_mfma_f32_16x16x32_bf16 v[42:45], v[154:157], v[212:215], 0
	v_mfma_f32_16x16x32_bf16 v[34:37], v[146:149], v[220:223], 0
	v_mfma_f32_16x16x32_bf16 v[26:29], v[154:157], v[220:223], 0
	v_mfma_f32_16x16x32_bf16 v[18:21], v[146:149], v[228:231], 0
	v_mfma_f32_16x16x32_bf16 v[10:13], v[154:157], v[228:231], 0
	v_mfma_f32_16x16x32_bf16 v[62:65], v[150:153], v[208:211], v[62:65]
	v_mfma_f32_16x16x32_bf16 v[58:61], v[158:161], v[208:211], v[58:61]
	v_mfma_f32_16x16x32_bf16 v[50:53], v[150:153], v[216:219], v[50:53]
	v_mfma_f32_16x16x32_bf16 v[42:45], v[158:161], v[216:219], v[42:45]
	v_mfma_f32_16x16x32_bf16 v[34:37], v[150:153], v[224:227], v[34:37]
	v_mfma_f32_16x16x32_bf16 v[26:29], v[158:161], v[224:227], v[26:29]
	v_mfma_f32_16x16x32_bf16 v[18:21], v[150:153], v[232:235], v[18:21]
	v_mfma_f32_16x16x32_bf16 v[10:13], v[158:161], v[232:235], v[10:13]
	s_setprio 0
	s_setprio 1
	v_mfma_f32_16x16x32_bf16 v[54:57], v[174:177], v[200:203], 0
	v_mfma_f32_16x16x32_bf16 v[46:49], v[182:185], v[200:203], 0
	v_mfma_f32_16x16x32_bf16 v[38:41], v[174:177], v[212:215], 0
	v_mfma_f32_16x16x32_bf16 v[30:33], v[182:185], v[212:215], 0
	v_mfma_f32_16x16x32_bf16 v[22:25], v[174:177], v[220:223], 0
	v_mfma_f32_16x16x32_bf16 v[14:17], v[182:185], v[220:223], 0
	v_mfma_f32_16x16x32_bf16 v[6:9], v[174:177], v[228:231], 0
	v_mfma_f32_16x16x32_bf16 v[2:5], v[182:185], v[228:231], 0
	v_mfma_f32_16x16x32_bf16 v[54:57], v[178:181], v[208:211], v[54:57]
	v_mfma_f32_16x16x32_bf16 v[46:49], v[186:189], v[208:211], v[46:49]
	v_mfma_f32_16x16x32_bf16 v[38:41], v[178:181], v[216:219], v[38:41]
	v_mfma_f32_16x16x32_bf16 v[30:33], v[186:189], v[216:219], v[30:33]
	v_mfma_f32_16x16x32_bf16 v[22:25], v[178:181], v[224:227], v[22:25]
	v_mfma_f32_16x16x32_bf16 v[14:17], v[186:189], v[224:227], v[14:17]
	v_mfma_f32_16x16x32_bf16 v[6:9], v[178:181], v[232:235], v[6:9]
	v_mfma_f32_16x16x32_bf16 v[2:5], v[186:189], v[232:235], v[2:5]
	s_setprio 0
	s_barrier
	s_add_i32 s70, 0, 0x18000
	s_add_i32 s71, 0, 0x1c000
	v_add_u32_e32 v158, s70, v143
	v_add_u32_e32 v186, s71, v143
	ds_read_b128 v[146:149], v158
	ds_read_b128 v[150:153], v158 offset:1024
	ds_read_b128 v[154:157], v158 offset:2048
	ds_read_b128 v[158:161], v158 offset:3072
	ds_read_b128 v[174:177], v186
	ds_read_b128 v[178:181], v186 offset:1024
	ds_read_b128 v[182:185], v186 offset:2048
	ds_read_b128 v[186:189], v186 offset:3072
	s_add_u32 s52, s52, 0x40000
	s_addc_u32 s53, s53, 0
	s_mov_b32 m0, s58
	v_lshl_add_u64 v[240:241], s[52:53], 0, v[134:135]
	ds_read_b128 v[200:203], v145 offset:32768
	ds_read_b128 v[208:211], v145 offset:33792
	ds_read_b128 v[212:215], v145 offset:34816
	ds_read_b128 v[216:219], v145 offset:35840
	ds_read_b128 v[220:223], v145 offset:36864
	ds_read_b128 v[224:227], v145 offset:37888
	ds_read_b128 v[228:231], v145 offset:38912
	ds_read_b128 v[232:235], v145 offset:39936
	global_load_lds_dwordx4 v[240:241], off
	v_lshl_add_u64 v[240:241], s[52:53], 0, v[132:133]
	s_mov_b32 m0, s59
	s_nop 0
	global_load_lds_dwordx4 v[240:241], off
	s_waitcnt vmcnt(8)
	s_waitcnt lgkmcnt(0)
	s_barrier
	s_setprio 1
	s_waitcnt lgkmcnt(0)
	v_mfma_f32_16x16x32_bf16 v[126:129], v[146:149], v[200:203], v[126:129]
	v_mfma_f32_16x16x32_bf16 v[122:125], v[154:157], v[200:203], v[122:125]
	v_mfma_f32_16x16x32_bf16 v[114:117], v[146:149], v[212:215], v[114:117]
	v_mfma_f32_16x16x32_bf16 v[106:109], v[154:157], v[212:215], v[106:109]
	v_mfma_f32_16x16x32_bf16 v[98:101], v[146:149], v[220:223], v[98:101]
	v_mfma_f32_16x16x32_bf16 v[90:93], v[154:157], v[220:223], v[90:93]
	v_mfma_f32_16x16x32_bf16 v[82:85], v[146:149], v[228:231], v[82:85]
	v_mfma_f32_16x16x32_bf16 v[74:77], v[154:157], v[228:231], v[74:77]
	v_mfma_f32_16x16x32_bf16 v[126:129], v[150:153], v[208:211], v[126:129]
	v_mfma_f32_16x16x32_bf16 v[122:125], v[158:161], v[208:211], v[122:125]
	v_mfma_f32_16x16x32_bf16 v[114:117], v[150:153], v[216:219], v[114:117]
	v_mfma_f32_16x16x32_bf16 v[106:109], v[158:161], v[216:219], v[106:109]
	v_mfma_f32_16x16x32_bf16 v[98:101], v[150:153], v[224:227], v[98:101]
	v_mfma_f32_16x16x32_bf16 v[90:93], v[158:161], v[224:227], v[90:93]
	v_mfma_f32_16x16x32_bf16 v[82:85], v[150:153], v[232:235], v[82:85]
	v_mfma_f32_16x16x32_bf16 v[74:77], v[158:161], v[232:235], v[74:77]
	s_setprio 0
	s_setprio 1
	v_mfma_f32_16x16x32_bf16 v[118:121], v[174:177], v[200:203], v[118:121]
	v_mfma_f32_16x16x32_bf16 v[110:113], v[182:185], v[200:203], v[110:113]
	v_mfma_f32_16x16x32_bf16 v[102:105], v[174:177], v[212:215], v[102:105]
	v_mfma_f32_16x16x32_bf16 v[94:97], v[182:185], v[212:215], v[94:97]
	v_mfma_f32_16x16x32_bf16 v[86:89], v[174:177], v[220:223], v[86:89]
	v_mfma_f32_16x16x32_bf16 v[78:81], v[182:185], v[220:223], v[78:81]
	v_mfma_f32_16x16x32_bf16 v[70:73], v[174:177], v[228:231], v[70:73]
	v_mfma_f32_16x16x32_bf16 v[66:69], v[182:185], v[228:231], v[66:69]
	v_mfma_f32_16x16x32_bf16 v[118:121], v[178:181], v[208:211], v[118:121]
	v_mfma_f32_16x16x32_bf16 v[110:113], v[186:189], v[208:211], v[110:113]
	v_mfma_f32_16x16x32_bf16 v[102:105], v[178:181], v[216:219], v[102:105]
	v_mfma_f32_16x16x32_bf16 v[94:97], v[186:189], v[216:219], v[94:97]
	v_mfma_f32_16x16x32_bf16 v[86:89], v[178:181], v[224:227], v[86:89]
	v_mfma_f32_16x16x32_bf16 v[78:81], v[186:189], v[224:227], v[78:81]
	v_mfma_f32_16x16x32_bf16 v[70:73], v[178:181], v[232:235], v[70:73]
	v_mfma_f32_16x16x32_bf16 v[66:69], v[186:189], v[232:235], v[66:69]
	s_setprio 0
	s_barrier
; #define PG8_STAGE(bufoff, gbase, voff) do { _Pragma("unroll") for (int _i = 0; _i < 2; ++_i) \
;         __builtin_amdgcn_global_load_lds((const unsigned*)((const char*)(gbase) + (voff)[_i]), (PG8_LAS unsigned*)(lds + (bufoff) + ldsw + _i * 8192), 16, 0, 0); } while (0)
; #define PG8_STAGEA(bufoff, gbase, voff) do { _Pragma("unroll") for (int _i = 0; _i < 2; ++_i) \
;         __builtin_amdgcn_global_load_lds((const unsigned*)((const char*)(gbase) + (voff)[_i]), (PG8_LAS unsigned*)(lds + (bufoff) + ldsw + _i * 8192), 16, 0, A_AUX); } while (0)
; #define PG8_LDA(dst, b, h) do { _Pragma("unroll") for (int m = 0; m < 4; ++m) _Pragma("unroll") for (int k = 0; k < 2; ++k) dst[m][k] = *(const PG8_LAS bf16x8*)(lds + PG8_SA(b, h) + aoff + m * 2048 + k * 1024); } while (0)
; #define PG8_MMA(ai, bj, At, Bt) do { __builtin_amdgcn_s_setprio(1); _Pragma("unroll") for (int m = 0; m < 4; ++m) _Pragma("unroll") for (int n = 0; n < 2; ++n) _Pragma("unroll") for (int k = 0; k < 2; ++k) \
;         acc[ai][bj][m][n] = __builtin_amdgcn_mfma_f32_16x16x32_bf16(Bt[n][k], At[m][k], acc[ai][bj][m][n], 0, 0, 0); __builtin_amdgcn_s_setprio(0); } while (0)
; #define PG8_WAIT_V(n) asm volatile("s_waitcnt vmcnt(" #n ")" ::: "memory")
; #define PG8_WAIT_L(n) asm volatile("s_waitcnt lgkmcnt(" #n ")" ::: "memory")
; #define PG8_BAR __builtin_amdgcn_s_barrier()
; #define PG8_SCHED __builtin_amdgcn_sched_barrier(0)
;     ...
;             PG8_LDA(At, 1, 1); PG8_STAGE(PG8_SB(1, 0), b3, voffB); PG8_STAGE(PG8_SB(1, 1), b3 + hstep, voffB); PG8_STAGEA(PG8_SA(1, 0), a3, voffA);
;             PG8_WAIT_V(8); PG8_WAIT_L(0); PG8_BAR; PG8_MMA(1, 0, At, B0); PG8_MMA(1, 1, At, B1); PG8_BAR; PG8_SCHED;
	s_add_i32 s52, s70, s55
	v_lshl_add_u64 v[140:141], v[140:141], 0, s[8:9]
	s_mov_b32 m0, s52
	ds_read_b128 v[200:203], v145 offset:49152
	ds_read_b128 v[208:211], v145 offset:50176
	ds_read_b128 v[212:215], v145 offset:51200
	ds_read_b128 v[216:219], v145 offset:52224
	ds_read_b128 v[220:223], v145 offset:53248
	ds_read_b128 v[224:227], v145 offset:54272
	ds_read_b128 v[228:231], v145 offset:55296
	ds_read_b128 v[232:235], v145 offset:56320
	global_load_lds_dwordx4 v[140:141], off
	s_add_i32 m0, s52, 0x2000
	s_add_u32 s50, s50, 0x40080
	v_lshl_add_u64 v[140:141], v[190:191], 0, s[8:9]
	s_addc_u32 s51, s51, 0
	s_add_i32 s52, s71, s55
	global_load_lds_dwordx4 v[140:141], off
	v_lshl_add_u64 v[140:141], s[50:51], 0, v[0:1]
	s_mov_b32 m0, s52
	s_nop 0
	global_load_lds_dwordx4 v[140:141], off
	v_lshl_add_u64 v[140:141], s[50:51], 0, v[130:131]
	s_add_i32 m0, s52, 0x2000
	s_nop 0
	global_load_lds_dwordx4 v[140:141], off
	v_lshl_add_u64 v[140:141], v[236:237], 0, s[8:9]
	s_mov_b32 m0, s60
	s_nop 0
	global_load_lds_dwordx4 v[140:141], off
	v_lshl_add_u64 v[140:141], v[238:239], 0, s[8:9]
	s_mov_b32 m0, s61
	s_nop 0
	global_load_lds_dwordx4 v[140:141], off
	s_waitcnt vmcnt(8)
	s_waitcnt lgkmcnt(0)
	s_barrier
	s_setprio 1
	s_waitcnt lgkmcnt(0)
	v_mfma_f32_16x16x32_bf16 v[62:65], v[146:149], v[200:203], v[62:65]
	v_mfma_f32_16x16x32_bf16 v[58:61], v[154:157], v[200:203], v[58:61]
	v_mfma_f32_16x16x32_bf16 v[50:53], v[146:149], v[212:215], v[50:53]
	v_mfma_f32_16x16x32_bf16 v[42:45], v[154:157], v[212:215], v[42:45]
	v_mfma_f32_16x16x32_bf16 v[34:37], v[146:149], v[220:223], v[34:37]
	v_mfma_f32_16x16x32_bf16 v[26:29], v[154:157], v[220:223], v[26:29]
	v_mfma_f32_16x16x32_bf16 v[18:21], v[146:149], v[228:231], v[18:21]
	v_mfma_f32_16x16x32_bf16 v[10:13], v[154:157], v[228:231], v[10:13]
	v_mfma_f32_16x16x32_bf16 v[62:65], v[150:153], v[208:211], v[62:65]
	v_mfma_f32_16x16x32_bf16 v[58:61], v[158:161], v[208:211], v[58:61]
	v_mfma_f32_16x16x32_bf16 v[50:53], v[150:153], v[216:219], v[50:53]
	v_mfma_f32_16x16x32_bf16 v[42:45], v[158:161], v[216:219], v[42:45]
	v_mfma_f32_16x16x32_bf16 v[34:37], v[150:153], v[224:227], v[34:37]
	v_mfma_f32_16x16x32_bf16 v[26:29], v[158:161], v[224:227], v[26:29]
	v_mfma_f32_16x16x32_bf16 v[18:21], v[150:153], v[232:235], v[18:21]
	v_mfma_f32_16x16x32_bf16 v[10:13], v[158:161], v[232:235], v[10:13]
	s_setprio 0
	s_setprio 1
	v_mfma_f32_16x16x32_bf16 v[54:57], v[174:177], v[200:203], v[54:57]
	v_mfma_f32_16x16x32_bf16 v[46:49], v[182:185], v[200:203], v[46:49]
	v_mfma_f32_16x16x32_bf16 v[38:41], v[174:177], v[212:215], v[38:41]
	v_mfma_f32_16x16x32_bf16 v[30:33], v[182:185], v[212:215], v[30:33]
	v_mfma_f32_16x16x32_bf16 v[22:25], v[174:177], v[220:223], v[22:25]
	v_mfma_f32_16x16x32_bf16 v[14:17], v[182:185], v[220:223], v[14:17]
	v_mfma_f32_16x16x32_bf16 v[6:9], v[174:177], v[228:231], v[6:9]
	v_mfma_f32_16x16x32_bf16 v[2:5], v[182:185], v[228:231], v[2:5]
	v_mfma_f32_16x16x32_bf16 v[54:57], v[178:181], v[208:211], v[54:57]
	v_mfma_f32_16x16x32_bf16 v[46:49], v[186:189], v[208:211], v[46:49]
	v_mfma_f32_16x16x32_bf16 v[38:41], v[178:181], v[216:219], v[38:41]
	v_mfma_f32_16x16x32_bf16 v[30:33], v[186:189], v[216:219], v[30:33]
	v_mfma_f32_16x16x32_bf16 v[22:25], v[178:181], v[224:227], v[22:25]
	v_mfma_f32_16x16x32_bf16 v[14:17], v[186:189], v[224:227], v[14:17]
	v_mfma_f32_16x16x32_bf16 v[6:9], v[178:181], v[232:235], v[6:9]
	v_mfma_f32_16x16x32_bf16 v[2:5], v[186:189], v[232:235], v[2:5]
	s_setprio 0
	s_barrier
	s_add_i32 s73, s73, 2
	s_add_u32 s48, s48, 0x100
	s_addc_u32 s49, s49, 0
	s_add_u32 s65, s65, 0x100
	s_addc_u32 s72, s72, 0
	.p2align 6

; #define PG8_STAGE(bufoff, gbase, voff) do { _Pragma("unroll") for (int _i = 0; _i < 2; ++_i) \
;         __builtin_amdgcn_global_load_lds((const unsigned*)((const char*)(gbase) + (voff)[_i]), (PG8_LAS unsigned*)(lds + (bufoff) + ldsw + _i * 8192), 16, 0, 0); } while (0)
; #define PG8_STAGEA(bufoff, gbase, voff) do { _Pragma("unroll") for (int _i = 0; _i < 2; ++_i) \
;         __builtin_amdgcn_global_load_lds((const unsigned*)((const char*)(gbase) + (voff)[_i]), (PG8_LAS unsigned*)(lds + (bufoff) + ldsw + _i * 8192), 16, 0, A_AUX); } while (0)
; #define PG8_LDA(dst, b, h) do { _Pragma("unroll") for (int m = 0; m < 4; ++m) _Pragma("unroll") for (int k = 0; k < 2; ++k) dst[m][k] = *(const PG8_LAS bf16x8*)(lds + PG8_SA(b, h) + aoff + m * 2048 + k * 1024); } while (0)
; #define PG8_LDB(dst, b, h) do { _Pragma("unroll") for (int n = 0; n < 2; ++n) _Pragma("unroll") for (int k = 0; k < 2; ++k) dst[n][k] = *(const PG8_LAS bf16x8*)(lds + PG8_SB(b, h) + boff + n * 2048 + k * 1024); } while (0)
; #define PG8_WAIT_V(n) asm volatile("s_waitcnt vmcnt(" #n ")" ::: "memory")
; #define PG8_WAIT_L(n) asm volatile("s_waitcnt lgkmcnt(" #n ")" ::: "memory")
; #define PG8_BAR __builtin_amdgcn_s_barrier()
;     ...
;         const bool has_next = S.next(ui + 1, nxt);
;         const char* nA = has_next ? (const char*)g.A + (size_t)nxt.pm * tstep : cA; const char* nB = has_next ? (const char*)g.Bt + (size_t)nxt.pn * tstep : cB;
;         for (int t = 0; t < nt; t += 2) {
;             const bool last = (t == nt - 2);
;             const char* a1 = cA + (size_t)(t + 1) * kstep;
;             const char* a2 = last ? nA : cA + (size_t)(t + 2) * kstep; const char* b2 = last ? nB : cB + (size_t)(t + 2) * kstep;
;             const char* a3 = a2 + kstep; const char* b3 = b2 + kstep;
;             if (last && has_next) S.a_ready(nxt);
;             if constexpr (SP2) {
;             PG8_LDB(B0, 0, 0); PG8_LDB(B1, 0, 1); PG8_SCHED; PG8_LDA(At, 0, 0); PG8_STAGEA(PG8_SA(1, 1), a1 + hstep, voffA);
;             PG8_WAIT_V(8); PG8_WAIT_L(0); PG8_BAR; PG8_MMA(0, 0, At, B0); PG8_MMA(0, 1, At, B1); PG8_BAR; PG8_SCHED;
;             PG8_LDA(At, 0, 1); PG8_STAGE(PG8_SB(0, 0), b2, voffB); PG8_STAGE(PG8_SB(0, 1), b2 + hstep, voffB); PG8_STAGEA(PG8_SA(0, 0), a2, voffA);
;             PG8_WAIT_V(8); PG8_WAIT_L(0); PG8_BAR; PG8_MMA(1, 0, At, B0); PG8_MMA(1, 1, At, B1); PG8_BAR; PG8_SCHED;
.LBB0_579:
	s_ashr_i32 s45, s44, 31
	s_lshl_b64 s[16:17], s[44:45], 19
	s_add_u32 s46, s97, s16
	s_addc_u32 s47, s29, s17
	s_and_b64 s[16:17], s[40:41], exec
	s_cselect_b32 s16, s47, s51
	s_cselect_b32 s17, s46, s50
	s_ashr_i32 s43, s42, 31
	s_lshl_b64 s[48:49], s[42:43], 19
	s_add_u32 s48, s23, s48
	s_addc_u32 s49, s56, s49
	s_and_b64 s[54:55], s[40:41], exec
	s_cselect_b32 s43, s49, s53
	s_cselect_b32 s45, s48, s52
	s_add_u32 s50, s50, 0x40080
	s_addc_u32 s51, s51, 0
	s_add_u32 s73, s52, 0x100
	s_addc_u32 s76, s53, 0
	s_mov_b32 vcc_lo, -2
	s_add_u32 s52, s50, 0xfffc0080
	s_addc_u32 s53, s51, -1
	s_add_i32 s70, 0, 0x10000
	s_cmp_eq_u32 vcc_lo, 12
	s_cselect_b32 s55, s16, s53
	s_cselect_b32 s54, s17, s52
	v_add_u32_e32 v140, s70, v143
	s_cselect_b32 s53, s43, s76
	s_cselect_b32 s52, s45, s73
	s_add_i32 vcc_hi, 0, 0x14000
	ds_read_b128 v[146:149], v140
	ds_read_b128 v[150:153], v140 offset:1024
	ds_read_b128 v[154:157], v140 offset:2048
	ds_read_b128 v[158:161], v140 offset:3072
	v_add_u32_e32 v140, vcc_hi, v143
	ds_read_b128 v[174:177], v140
	ds_read_b128 v[178:181], v140 offset:1024
	ds_read_b128 v[182:185], v140 offset:2048
	ds_read_b128 v[186:189], v140 offset:3072
	v_lshl_add_u64 v[140:141], s[50:51], 0, v[136:137]
	s_add_i32 m0, s58, 0xc000
	ds_read_b128 v[200:203], v145
	ds_read_b128 v[208:211], v145 offset:1024
	ds_read_b128 v[212:215], v145 offset:2048
	ds_read_b128 v[216:219], v145 offset:3072
	ds_read_b128 v[220:223], v145 offset:4096
	ds_read_b128 v[224:227], v145 offset:5120
	ds_read_b128 v[228:231], v145 offset:6144
	ds_read_b128 v[232:235], v145 offset:7168
	global_load_lds_dwordx4 v[140:141], off
	v_lshl_add_u64 v[140:141], s[50:51], 0, v[138:139]
	s_add_i32 m0, s58, 0xe000
	s_nop 0
	global_load_lds_dwordx4 v[140:141], off
	s_waitcnt vmcnt(8)
	s_waitcnt lgkmcnt(0)
	s_barrier
	s_setprio 1
	s_waitcnt lgkmcnt(0)
	v_mfma_f32_16x16x32_bf16 v[126:129], v[146:149], v[200:203], 0
	v_mfma_f32_16x16x32_bf16 v[122:125], v[154:157], v[200:203], 0
	v_mfma_f32_16x16x32_bf16 v[110:113], v[146:149], v[212:215], 0
	v_mfma_f32_16x16x32_bf16 v[106:109], v[154:157], v[212:215], 0
	v_mfma_f32_16x16x32_bf16 v[94:97], v[146:149], v[220:223], 0
	v_mfma_f32_16x16x32_bf16 v[90:93], v[154:157], v[220:223], 0
	v_mfma_f32_16x16x32_bf16 v[78:81], v[146:149], v[228:231], 0
	v_mfma_f32_16x16x32_bf16 v[74:77], v[154:157], v[228:231], 0
	v_mfma_f32_16x16x32_bf16 v[126:129], v[150:153], v[208:211], v[126:129]
	v_mfma_f32_16x16x32_bf16 v[122:125], v[158:161], v[208:211], v[122:125]
	v_mfma_f32_16x16x32_bf16 v[110:113], v[150:153], v[216:219], v[110:113]
	v_mfma_f32_16x16x32_bf16 v[106:109], v[158:161], v[216:219], v[106:109]
	v_mfma_f32_16x16x32_bf16 v[94:97], v[150:153], v[224:227], v[94:97]
	v_mfma_f32_16x16x32_bf16 v[90:93], v[158:161], v[224:227], v[90:93]
	v_mfma_f32_16x16x32_bf16 v[78:81], v[150:153], v[232:235], v[78:81]
	v_mfma_f32_16x16x32_bf16 v[74:77], v[158:161], v[232:235], v[74:77]
	s_setprio 0
	s_setprio 1
	v_mfma_f32_16x16x32_bf16 v[118:121], v[174:177], v[200:203], 0
	v_mfma_f32_16x16x32_bf16 v[114:117], v[182:185], v[200:203], 0
	v_mfma_f32_16x16x32_bf16 v[102:105], v[174:177], v[212:215], 0
	v_mfma_f32_16x16x32_bf16 v[98:101], v[182:185], v[212:215], 0
	v_mfma_f32_16x16x32_bf16 v[86:89], v[174:177], v[220:223], 0
	v_mfma_f32_16x16x32_bf16 v[82:85], v[182:185], v[220:223], 0
	v_mfma_f32_16x16x32_bf16 v[70:73], v[174:177], v[228:231], 0
	v_mfma_f32_16x16x32_bf16 v[66:69], v[182:185], v[228:231], 0
	v_mfma_f32_16x16x32_bf16 v[118:121], v[178:181], v[208:211], v[118:121]
	v_mfma_f32_16x16x32_bf16 v[114:117], v[186:189], v[208:211], v[114:117]
	v_mfma_f32_16x16x32_bf16 v[102:105], v[178:181], v[216:219], v[102:105]
	v_mfma_f32_16x16x32_bf16 v[98:101], v[186:189], v[216:219], v[98:101]
	v_mfma_f32_16x16x32_bf16 v[86:89], v[178:181], v[224:227], v[86:89]
	v_mfma_f32_16x16x32_bf16 v[82:85], v[186:189], v[224:227], v[82:85]
	v_mfma_f32_16x16x32_bf16 v[70:73], v[178:181], v[232:235], v[70:73]
	v_mfma_f32_16x16x32_bf16 v[66:69], v[186:189], v[232:235], v[66:69]
	s_setprio 0
	s_barrier
	s_add_i32 s70, s70, s57
	v_lshl_add_u64 v[140:141], s[52:53], 0, v[0:1]
	s_mov_b32 m0, s70
	ds_read_b128 v[200:203], v145 offset:16384
	ds_read_b128 v[208:211], v145 offset:17408
	ds_read_b128 v[212:215], v145 offset:18432
	ds_read_b128 v[216:219], v145 offset:19456
	ds_read_b128 v[220:223], v145 offset:20480
	ds_read_b128 v[224:227], v145 offset:21504
	ds_read_b128 v[228:231], v145 offset:22528
	ds_read_b128 v[232:235], v145 offset:23552
	global_load_lds_dwordx4 v[140:141], off
	s_add_i32 m0, s70, 0x2000
	s_add_u32 s70, s52, 0x40000
	v_lshl_add_u64 v[190:191], s[52:53], 0, v[130:131]
	s_addc_u32 s71, s53, 0
	s_add_i32 vcc_hi, vcc_hi, s57
	global_load_lds_dwordx4 v[190:191], off
	v_lshl_add_u64 v[236:237], s[70:71], 0, v[0:1]
	s_mov_b32 m0, vcc_hi
	v_lshl_add_u64 v[238:239], s[54:55], 0, v[132:133]
	global_load_lds_dwordx4 v[236:237], off
	v_lshl_add_u64 v[236:237], s[70:71], 0, v[130:131]
	s_add_i32 m0, vcc_hi, 0x2000
	s_nop 0
	global_load_lds_dwordx4 v[236:237], off
	v_lshl_add_u64 v[236:237], s[54:55], 0, v[134:135]
	s_mov_b32 m0, s58
	s_nop 0
	global_load_lds_dwordx4 v[236:237], off
	s_mov_b32 m0, s59
	s_nop 0
	global_load_lds_dwordx4 v[238:239], off
	s_waitcnt vmcnt(8)
	s_waitcnt lgkmcnt(0)
	s_barrier
; #define PG8_STAGEA(bufoff, gbase, voff) do { _Pragma("unroll") for (int _i = 0; _i < 2; ++_i) \
;         __builtin_amdgcn_global_load_lds((const unsigned*)((const char*)(gbase) + (voff)[_i]), (PG8_LAS unsigned*)(lds + (bufoff) + ldsw + _i * 8192), 16, 0, A_AUX); } while (0)
; #define PG8_LDA(dst, b, h) do { _Pragma("unroll") for (int m = 0; m < 4; ++m) _Pragma("unroll") for (int k = 0; k < 2; ++k) dst[m][k] = *(const PG8_LAS bf16x8*)(lds + PG8_SA(b, h) + aoff + m * 2048 + k * 1024); } while (0)
; #define PG8_LDB(dst, b, h) do { _Pragma("unroll") for (int n = 0; n < 2; ++n) _Pragma("unroll") for (int k = 0; k < 2; ++k) dst[n][k] = *(const PG8_LAS bf16x8*)(lds + PG8_SB(b, h) + boff + n * 2048 + k * 1024); } while (0)
; #define PG8_MMA(ai, bj, At, Bt) do { __builtin_amdgcn_s_setprio(1); _Pragma("unroll") for (int m = 0; m < 4; ++m) _Pragma("unroll") for (int n = 0; n < 2; ++n) _Pragma("unroll") for (int k = 0; k < 2; ++k) \
;         acc[ai][bj][m][n] = __builtin_amdgcn_mfma_f32_16x16x32_bf16(Bt[n][k], At[m][k], acc[ai][bj][m][n], 0, 0, 0); __builtin_amdgcn_s_setprio(0); } while (0)
; #define PG8_WAIT_V(n) asm volatile("s_waitcnt vmcnt(" #n ")" ::: "memory")
; #define PG8_WAIT_L(n) asm volatile("s_waitcnt lgkmcnt(" #n ")" ::: "memory")
; #define PG8_BAR __builtin_amdgcn_s_barrier()
; #define PG8_SCHED __builtin_amdgcn_sched_barrier(0)
;     ...
;             PG8_WAIT_V(8); PG8_WAIT_L(0); PG8_BAR; PG8_MMA(1, 0, At, B0); PG8_MMA(1, 1, At, B1); PG8_BAR; PG8_SCHED;
;             PG8_LDB(B0, 1, 0); PG8_LDB(B1, 1, 1); PG8_SCHED; PG8_LDA(At, 1, 0); PG8_STAGEA(PG8_SA(0, 1), a2 + hstep, voffA);
;             PG8_WAIT_V(8); PG8_WAIT_L(0); PG8_BAR; PG8_MMA(0, 0, At, B0); PG8_MMA(0, 1, At, B1); PG8_BAR; PG8_SCHED;
	s_setprio 1
	s_waitcnt lgkmcnt(0)
	v_mfma_f32_16x16x32_bf16 v[62:65], v[146:149], v[200:203], 0
	v_mfma_f32_16x16x32_bf16 v[58:61], v[154:157], v[200:203], 0
	v_mfma_f32_16x16x32_bf16 v[46:49], v[146:149], v[212:215], 0
	v_mfma_f32_16x16x32_bf16 v[42:45], v[154:157], v[212:215], 0
	v_mfma_f32_16x16x32_bf16 v[30:33], v[146:149], v[220:223], 0
	v_mfma_f32_16x16x32_bf16 v[26:29], v[154:157], v[220:223], 0
	v_mfma_f32_16x16x32_bf16 v[14:17], v[146:149], v[228:231], 0
	v_mfma_f32_16x16x32_bf16 v[10:13], v[154:157], v[228:231], 0
	v_mfma_f32_16x16x32_bf16 v[62:65], v[150:153], v[208:211], v[62:65]
	v_mfma_f32_16x16x32_bf16 v[58:61], v[158:161], v[208:211], v[58:61]
	v_mfma_f32_16x16x32_bf16 v[46:49], v[150:153], v[216:219], v[46:49]
	v_mfma_f32_16x16x32_bf16 v[42:45], v[158:161], v[216:219], v[42:45]
	v_mfma_f32_16x16x32_bf16 v[30:33], v[150:153], v[224:227], v[30:33]
	v_mfma_f32_16x16x32_bf16 v[26:29], v[158:161], v[224:227], v[26:29]
	v_mfma_f32_16x16x32_bf16 v[14:17], v[150:153], v[232:235], v[14:17]
	v_mfma_f32_16x16x32_bf16 v[10:13], v[158:161], v[232:235], v[10:13]
	s_setprio 0
	s_setprio 1
	v_mfma_f32_16x16x32_bf16 v[54:57], v[174:177], v[200:203], 0
	v_mfma_f32_16x16x32_bf16 v[50:53], v[182:185], v[200:203], 0
	v_mfma_f32_16x16x32_bf16 v[38:41], v[174:177], v[212:215], 0
	v_mfma_f32_16x16x32_bf16 v[34:37], v[182:185], v[212:215], 0
	v_mfma_f32_16x16x32_bf16 v[22:25], v[174:177], v[220:223], 0
	v_mfma_f32_16x16x32_bf16 v[18:21], v[182:185], v[220:223], 0
	v_mfma_f32_16x16x32_bf16 v[6:9], v[174:177], v[228:231], 0
	v_mfma_f32_16x16x32_bf16 v[2:5], v[182:185], v[228:231], 0
	v_mfma_f32_16x16x32_bf16 v[54:57], v[178:181], v[208:211], v[54:57]
	v_mfma_f32_16x16x32_bf16 v[50:53], v[186:189], v[208:211], v[50:53]
	v_mfma_f32_16x16x32_bf16 v[38:41], v[178:181], v[216:219], v[38:41]
	v_mfma_f32_16x16x32_bf16 v[34:37], v[186:189], v[216:219], v[34:37]
	v_mfma_f32_16x16x32_bf16 v[22:25], v[178:181], v[224:227], v[22:25]
	v_mfma_f32_16x16x32_bf16 v[18:21], v[186:189], v[224:227], v[18:21]
	v_mfma_f32_16x16x32_bf16 v[6:9], v[178:181], v[232:235], v[6:9]
	v_mfma_f32_16x16x32_bf16 v[2:5], v[186:189], v[232:235], v[2:5]
	s_setprio 0
	s_barrier
	s_add_i32 s70, 0, 0x18000
	s_add_i32 s71, 0, 0x1c000
	v_add_u32_e32 v158, s70, v143
	v_add_u32_e32 v186, s71, v143
	ds_read_b128 v[146:149], v158
	ds_read_b128 v[150:153], v158 offset:1024
	ds_read_b128 v[154:157], v158 offset:2048
	ds_read_b128 v[158:161], v158 offset:3072
	ds_read_b128 v[174:177], v186
	ds_read_b128 v[178:181], v186 offset:1024
	ds_read_b128 v[182:185], v186 offset:2048
	ds_read_b128 v[186:189], v186 offset:3072
	s_add_u32 s54, s54, 0x40000
	s_addc_u32 s55, s55, 0
	s_mov_b32 m0, s60
	v_lshl_add_u64 v[240:241], s[54:55], 0, v[134:135]
	ds_read_b128 v[200:203], v145 offset:32768
	ds_read_b128 v[208:211], v145 offset:33792
	ds_read_b128 v[212:215], v145 offset:34816
	ds_read_b128 v[216:219], v145 offset:35840
	ds_read_b128 v[220:223], v145 offset:36864
	ds_read_b128 v[224:227], v145 offset:37888
	ds_read_b128 v[228:231], v145 offset:38912
	ds_read_b128 v[232:235], v145 offset:39936
	global_load_lds_dwordx4 v[240:241], off
	v_lshl_add_u64 v[240:241], s[54:55], 0, v[132:133]
	s_mov_b32 m0, s61
	s_nop 0
	global_load_lds_dwordx4 v[240:241], off
	s_waitcnt vmcnt(8)
	s_waitcnt lgkmcnt(0)
	s_barrier
	s_setprio 1
	s_waitcnt lgkmcnt(0)
	v_mfma_f32_16x16x32_bf16 v[126:129], v[146:149], v[200:203], v[126:129]
	v_mfma_f32_16x16x32_bf16 v[122:125], v[154:157], v[200:203], v[122:125]
	v_mfma_f32_16x16x32_bf16 v[110:113], v[146:149], v[212:215], v[110:113]
	v_mfma_f32_16x16x32_bf16 v[106:109], v[154:157], v[212:215], v[106:109]
	v_mfma_f32_16x16x32_bf16 v[94:97], v[146:149], v[220:223], v[94:97]
	v_mfma_f32_16x16x32_bf16 v[90:93], v[154:157], v[220:223], v[90:93]
	v_mfma_f32_16x16x32_bf16 v[78:81], v[146:149], v[228:231], v[78:81]
	v_mfma_f32_16x16x32_bf16 v[74:77], v[154:157], v[228:231], v[74:77]
	v_mfma_f32_16x16x32_bf16 v[126:129], v[150:153], v[208:211], v[126:129]
	v_mfma_f32_16x16x32_bf16 v[122:125], v[158:161], v[208:211], v[122:125]
	v_mfma_f32_16x16x32_bf16 v[110:113], v[150:153], v[216:219], v[110:113]
	v_mfma_f32_16x16x32_bf16 v[106:109], v[158:161], v[216:219], v[106:109]
	v_mfma_f32_16x16x32_bf16 v[94:97], v[150:153], v[224:227], v[94:97]
	v_mfma_f32_16x16x32_bf16 v[90:93], v[158:161], v[224:227], v[90:93]
	v_mfma_f32_16x16x32_bf16 v[78:81], v[150:153], v[232:235], v[78:81]
	v_mfma_f32_16x16x32_bf16 v[74:77], v[158:161], v[232:235], v[74:77]
	s_setprio 0
	s_setprio 1
	v_mfma_f32_16x16x32_bf16 v[118:121], v[174:177], v[200:203], v[118:121]
	v_mfma_f32_16x16x32_bf16 v[114:117], v[182:185], v[200:203], v[114:117]
	v_mfma_f32_16x16x32_bf16 v[102:105], v[174:177], v[212:215], v[102:105]
	v_mfma_f32_16x16x32_bf16 v[98:101], v[182:185], v[212:215], v[98:101]
	v_mfma_f32_16x16x32_bf16 v[86:89], v[174:177], v[220:223], v[86:89]
	v_mfma_f32_16x16x32_bf16 v[82:85], v[182:185], v[220:223], v[82:85]
	v_mfma_f32_16x16x32_bf16 v[70:73], v[174:177], v[228:231], v[70:73]
	v_mfma_f32_16x16x32_bf16 v[66:69], v[182:185], v[228:231], v[66:69]
	v_mfma_f32_16x16x32_bf16 v[118:121], v[178:181], v[208:211], v[118:121]
	v_mfma_f32_16x16x32_bf16 v[114:117], v[186:189], v[208:211], v[114:117]
	v_mfma_f32_16x16x32_bf16 v[102:105], v[178:181], v[216:219], v[102:105]
	v_mfma_f32_16x16x32_bf16 v[98:101], v[186:189], v[216:219], v[98:101]
	v_mfma_f32_16x16x32_bf16 v[86:89], v[178:181], v[224:227], v[86:89]
	v_mfma_f32_16x16x32_bf16 v[82:85], v[186:189], v[224:227], v[82:85]
	v_mfma_f32_16x16x32_bf16 v[70:73], v[178:181], v[232:235], v[70:73]
	v_mfma_f32_16x16x32_bf16 v[66:69], v[186:189], v[232:235], v[66:69]
	s_setprio 0
	s_barrier
; #define PG8_STAGE(bufoff, gbase, voff) do { _Pragma("unroll") for (int _i = 0; _i < 2; ++_i) \
;         __builtin_amdgcn_global_load_lds((const unsigned*)((const char*)(gbase) + (voff)[_i]), (PG8_LAS unsigned*)(lds + (bufoff) + ldsw + _i * 8192), 16, 0, 0); } while (0)
; #define PG8_STAGEA(bufoff, gbase, voff) do { _Pragma("unroll") for (int _i = 0; _i < 2; ++_i) \
;         __builtin_amdgcn_global_load_lds((const unsigned*)((const char*)(gbase) + (voff)[_i]), (PG8_LAS unsigned*)(lds + (bufoff) + ldsw + _i * 8192), 16, 0, A_AUX); } while (0)
; #define PG8_LDA(dst, b, h) do { _Pragma("unroll") for (int m = 0; m < 4; ++m) _Pragma("unroll") for (int k = 0; k < 2; ++k) dst[m][k] = *(const PG8_LAS bf16x8*)(lds + PG8_SA(b, h) + aoff + m * 2048 + k * 1024); } while (0)
; #define PG8_MMA(ai, bj, At, Bt) do { __builtin_amdgcn_s_setprio(1); _Pragma("unroll") for (int m = 0; m < 4; ++m) _Pragma("unroll") for (int n = 0; n < 2; ++n) _Pragma("unroll") for (int k = 0; k < 2; ++k) \
;         acc[ai][bj][m][n] = __builtin_amdgcn_mfma_f32_16x16x32_bf16(Bt[n][k], At[m][k], acc[ai][bj][m][n], 0, 0, 0); __builtin_amdgcn_s_setprio(0); } while (0)
; #define PG8_WAIT_V(n) asm volatile("s_waitcnt vmcnt(" #n ")" ::: "memory")
; #define PG8_WAIT_L(n) asm volatile("s_waitcnt lgkmcnt(" #n ")" ::: "memory")
; #define PG8_BAR __builtin_amdgcn_s_barrier()
; #define PG8_SCHED __builtin_amdgcn_sched_barrier(0)
;     ...
;             PG8_LDA(At, 1, 1); PG8_STAGE(PG8_SB(1, 0), b3, voffB); PG8_STAGE(PG8_SB(1, 1), b3 + hstep, voffB); PG8_STAGEA(PG8_SA(1, 0), a3, voffA);
;             PG8_WAIT_V(8); PG8_WAIT_L(0); PG8_BAR; PG8_MMA(1, 0, At, B0); PG8_MMA(1, 1, At, B1); PG8_BAR; PG8_SCHED;
	s_add_i32 s54, s70, s57
	v_lshl_add_u64 v[140:141], v[140:141], 0, s[8:9]
	s_mov_b32 m0, s54
	ds_read_b128 v[200:203], v145 offset:49152
	ds_read_b128 v[208:211], v145 offset:50176
	ds_read_b128 v[212:215], v145 offset:51200
	ds_read_b128 v[216:219], v145 offset:52224
	ds_read_b128 v[220:223], v145 offset:53248
	ds_read_b128 v[224:227], v145 offset:54272
	ds_read_b128 v[228:231], v145 offset:55296
	ds_read_b128 v[232:235], v145 offset:56320
	global_load_lds_dwordx4 v[140:141], off
	s_add_i32 m0, s54, 0x2000
	s_add_u32 s52, s52, 0x40080
	v_lshl_add_u64 v[140:141], v[190:191], 0, s[8:9]
	s_addc_u32 s53, s53, 0
	s_add_i32 s54, s71, s57
	global_load_lds_dwordx4 v[140:141], off
	v_lshl_add_u64 v[140:141], s[52:53], 0, v[0:1]
	s_mov_b32 m0, s54
	s_nop 0
	global_load_lds_dwordx4 v[140:141], off
	v_lshl_add_u64 v[140:141], s[52:53], 0, v[130:131]
	s_add_i32 m0, s54, 0x2000
	s_nop 0
	global_load_lds_dwordx4 v[140:141], off
	v_lshl_add_u64 v[140:141], v[236:237], 0, s[8:9]
	s_mov_b32 m0, s62
	s_nop 0
	global_load_lds_dwordx4 v[140:141], off
	v_lshl_add_u64 v[140:141], v[238:239], 0, s[8:9]
	s_mov_b32 m0, s63
	s_nop 0
	global_load_lds_dwordx4 v[140:141], off
	s_waitcnt vmcnt(8)
	s_waitcnt lgkmcnt(0)
	s_barrier
	s_setprio 1
	s_waitcnt lgkmcnt(0)
	v_mfma_f32_16x16x32_bf16 v[62:65], v[146:149], v[200:203], v[62:65]
	v_mfma_f32_16x16x32_bf16 v[58:61], v[154:157], v[200:203], v[58:61]
	v_mfma_f32_16x16x32_bf16 v[46:49], v[146:149], v[212:215], v[46:49]
	v_mfma_f32_16x16x32_bf16 v[42:45], v[154:157], v[212:215], v[42:45]
	v_mfma_f32_16x16x32_bf16 v[30:33], v[146:149], v[220:223], v[30:33]
	v_mfma_f32_16x16x32_bf16 v[26:29], v[154:157], v[220:223], v[26:29]
	v_mfma_f32_16x16x32_bf16 v[14:17], v[146:149], v[228:231], v[14:17]
	v_mfma_f32_16x16x32_bf16 v[10:13], v[154:157], v[228:231], v[10:13]
	v_mfma_f32_16x16x32_bf16 v[62:65], v[150:153], v[208:211], v[62:65]
	v_mfma_f32_16x16x32_bf16 v[58:61], v[158:161], v[208:211], v[58:61]
	v_mfma_f32_16x16x32_bf16 v[46:49], v[150:153], v[216:219], v[46:49]
	v_mfma_f32_16x16x32_bf16 v[42:45], v[158:161], v[216:219], v[42:45]
	v_mfma_f32_16x16x32_bf16 v[30:33], v[150:153], v[224:227], v[30:33]
	v_mfma_f32_16x16x32_bf16 v[26:29], v[158:161], v[224:227], v[26:29]
	v_mfma_f32_16x16x32_bf16 v[14:17], v[150:153], v[232:235], v[14:17]
	v_mfma_f32_16x16x32_bf16 v[10:13], v[158:161], v[232:235], v[10:13]
	s_setprio 0
	s_setprio 1
	v_mfma_f32_16x16x32_bf16 v[54:57], v[174:177], v[200:203], v[54:57]
	v_mfma_f32_16x16x32_bf16 v[50:53], v[182:185], v[200:203], v[50:53]
	v_mfma_f32_16x16x32_bf16 v[38:41], v[174:177], v[212:215], v[38:41]
	v_mfma_f32_16x16x32_bf16 v[34:37], v[182:185], v[212:215], v[34:37]
	v_mfma_f32_16x16x32_bf16 v[22:25], v[174:177], v[220:223], v[22:25]
	v_mfma_f32_16x16x32_bf16 v[18:21], v[182:185], v[220:223], v[18:21]
	v_mfma_f32_16x16x32_bf16 v[6:9], v[174:177], v[228:231], v[6:9]
	v_mfma_f32_16x16x32_bf16 v[2:5], v[182:185], v[228:231], v[2:5]
	v_mfma_f32_16x16x32_bf16 v[54:57], v[178:181], v[208:211], v[54:57]
	v_mfma_f32_16x16x32_bf16 v[50:53], v[186:189], v[208:211], v[50:53]
	v_mfma_f32_16x16x32_bf16 v[38:41], v[178:181], v[216:219], v[38:41]
	v_mfma_f32_16x16x32_bf16 v[34:37], v[186:189], v[216:219], v[34:37]
	v_mfma_f32_16x16x32_bf16 v[22:25], v[178:181], v[224:227], v[22:25]
	v_mfma_f32_16x16x32_bf16 v[18:21], v[186:189], v[224:227], v[18:21]
	v_mfma_f32_16x16x32_bf16 v[6:9], v[178:181], v[232:235], v[6:9]
	v_mfma_f32_16x16x32_bf16 v[2:5], v[186:189], v[232:235], v[2:5]
	s_setprio 0
	s_barrier
	s_add_i32 vcc_lo, vcc_lo, 2
	s_add_u32 s50, s50, 0x100
	s_addc_u32 s51, s51, 0
	s_add_u32 s73, s73, 0x100
	s_addc_u32 s76, s76, 0
	.p2align 6

; #define PG8_STAGE(bufoff, gbase, voff) do { _Pragma("unroll") for (int _i = 0; _i < 2; ++_i) \
;         __builtin_amdgcn_global_load_lds((const unsigned*)((const char*)(gbase) + (voff)[_i]), (PG8_LAS unsigned*)(lds + (bufoff) + ldsw + _i * 8192), 16, 0, 0); } while (0)
; #define PG8_STAGEA(bufoff, gbase, voff) do { _Pragma("unroll") for (int _i = 0; _i < 2; ++_i) \
;         __builtin_amdgcn_global_load_lds((const unsigned*)((const char*)(gbase) + (voff)[_i]), (PG8_LAS unsigned*)(lds + (bufoff) + ldsw + _i * 8192), 16, 0, A_AUX); } while (0)
; #define PG8_LDA(dst, b, h) do { _Pragma("unroll") for (int m = 0; m < 4; ++m) _Pragma("unroll") for (int k = 0; k < 2; ++k) dst[m][k] = *(const PG8_LAS bf16x8*)(lds + PG8_SA(b, h) + aoff + m * 2048 + k * 1024); } while (0)
; #define PG8_LDB(dst, b, h) do { _Pragma("unroll") for (int n = 0; n < 2; ++n) _Pragma("unroll") for (int k = 0; k < 2; ++k) dst[n][k] = *(const PG8_LAS bf16x8*)(lds + PG8_SB(b, h) + boff + n * 2048 + k * 1024); } while (0)
; #define PG8_MMA(ai, bj, At, Bt) do { __builtin_amdgcn_s_setprio(1); _Pragma("unroll") for (int m = 0; m < 4; ++m) _Pragma("unroll") for (int n = 0; n < 2; ++n) _Pragma("unroll") for (int k = 0; k < 2; ++k) \
;         acc[ai][bj][m][n] = __builtin_amdgcn_mfma_f32_16x16x32_bf16(Bt[n][k], At[m][k], acc[ai][bj][m][n], 0, 0, 0); __builtin_amdgcn_s_setprio(0); } while (0)
; #define PG8_BAR __builtin_amdgcn_s_barrier()
;     ...
;         for (int t = 0; t < nt; t += 2) {
;             const bool last = (t == nt - 2);
;             const char* a1 = cA + (size_t)(t + 1) * kstep;
;             const char* a2 = last ? nA : cA + (size_t)(t + 2) * kstep; const char* b2 = last ? nB : cB + (size_t)(t + 2) * kstep;
;             const char* a3 = a2 + kstep; const char* b3 = b2 + kstep;
;             if (last && has_next) S.a_ready(nxt);
;             if constexpr (SP2) {
;             PG8_LDB(B0, 0, 0); PG8_LDB(B1, 0, 1); PG8_SCHED; PG8_LDA(At, 0, 0); PG8_STAGEA(PG8_SA(1, 1), a1 + hstep, voffA);
;             PG8_WAIT_V(8); PG8_WAIT_L(0); PG8_BAR; PG8_MMA(0, 0, At, B0); PG8_MMA(0, 1, At, B1); PG8_BAR; PG8_SCHED;
;             PG8_LDA(At, 0, 1); PG8_STAGE(PG8_SB(0, 0), b2, voffB); PG8_STAGE(PG8_SB(0, 1), b2 + hstep, voffB); PG8_STAGEA(PG8_SA(0, 0), a2, voffA);
;             PG8_WAIT_V(8); PG8_WAIT_L(0); PG8_BAR; PG8_MMA(1, 0, At, B0); PG8_MMA(1, 1, At, B1); PG8_BAR; PG8_SCHED;
.LBB0_655:
	s_add_u32 s16, s48, 0x100
	s_addc_u32 s17, s49, 0
	s_mov_b32 s73, -2
	s_add_u32 s48, s46, 0x100
	s_addc_u32 s49, s47, 0
	s_add_i32 s70, 0, 0x10000
	s_cmp_eq_u32 s73, 40
	s_cselect_b32 s53, s1, s49
	s_cselect_b32 s52, s0, s48
	v_add_u32_e32 v140, s70, v143
	s_cselect_b32 s51, s45, s17
	s_cselect_b32 s50, s44, s16
	s_add_i32 s71, 0, 0x14000
	ds_read_b128 v[146:149], v140
	ds_read_b128 v[150:153], v140 offset:1024
	ds_read_b128 v[154:157], v140 offset:2048
	ds_read_b128 v[158:161], v140 offset:3072
	v_add_u32_e32 v140, s71, v143
	ds_read_b128 v[174:177], v140
	ds_read_b128 v[178:181], v140 offset:1024
	ds_read_b128 v[182:185], v140 offset:2048
	ds_read_b128 v[186:189], v140 offset:3072
	v_lshl_add_u64 v[140:141], s[46:47], 0, v[136:137]
	s_add_i32 m0, s56, 0xc000
	ds_read_b128 v[200:203], v145
	ds_read_b128 v[208:211], v145 offset:1024
	ds_read_b128 v[212:215], v145 offset:2048
	ds_read_b128 v[216:219], v145 offset:3072
	ds_read_b128 v[220:223], v145 offset:4096
	ds_read_b128 v[224:227], v145 offset:5120
	ds_read_b128 v[228:231], v145 offset:6144
	ds_read_b128 v[232:235], v145 offset:7168
	global_load_lds_dwordx4 v[140:141], off
	v_lshl_add_u64 v[140:141], s[46:47], 0, v[138:139]
	s_add_i32 m0, s56, 0xe000
	s_nop 0
	global_load_lds_dwordx4 v[140:141], off
	s_waitcnt vmcnt(8)
	s_waitcnt lgkmcnt(0)
	s_barrier
	s_setprio 1
	s_waitcnt lgkmcnt(0)
	v_mfma_f32_16x16x32_bf16 v[126:129], v[146:149], v[200:203], 0
	v_mfma_f32_16x16x32_bf16 v[122:125], v[154:157], v[200:203], 0
	v_mfma_f32_16x16x32_bf16 v[114:117], v[146:149], v[212:215], 0
	v_mfma_f32_16x16x32_bf16 v[106:109], v[154:157], v[212:215], 0
	v_mfma_f32_16x16x32_bf16 v[98:101], v[146:149], v[220:223], 0
	v_mfma_f32_16x16x32_bf16 v[90:93], v[154:157], v[220:223], 0
	v_mfma_f32_16x16x32_bf16 v[82:85], v[146:149], v[228:231], 0
	v_mfma_f32_16x16x32_bf16 v[74:77], v[154:157], v[228:231], 0
	v_mfma_f32_16x16x32_bf16 v[126:129], v[150:153], v[208:211], v[126:129]
	v_mfma_f32_16x16x32_bf16 v[122:125], v[158:161], v[208:211], v[122:125]
	v_mfma_f32_16x16x32_bf16 v[114:117], v[150:153], v[216:219], v[114:117]
	v_mfma_f32_16x16x32_bf16 v[106:109], v[158:161], v[216:219], v[106:109]
	v_mfma_f32_16x16x32_bf16 v[98:101], v[150:153], v[224:227], v[98:101]
	v_mfma_f32_16x16x32_bf16 v[90:93], v[158:161], v[224:227], v[90:93]
	v_mfma_f32_16x16x32_bf16 v[82:85], v[150:153], v[232:235], v[82:85]
	v_mfma_f32_16x16x32_bf16 v[74:77], v[158:161], v[232:235], v[74:77]
	s_setprio 0
	s_setprio 1
	v_mfma_f32_16x16x32_bf16 v[118:121], v[174:177], v[200:203], 0
	v_mfma_f32_16x16x32_bf16 v[110:113], v[182:185], v[200:203], 0
	v_mfma_f32_16x16x32_bf16 v[102:105], v[174:177], v[212:215], 0
	v_mfma_f32_16x16x32_bf16 v[94:97], v[182:185], v[212:215], 0
	v_mfma_f32_16x16x32_bf16 v[86:89], v[174:177], v[220:223], 0
	v_mfma_f32_16x16x32_bf16 v[78:81], v[182:185], v[220:223], 0
	v_mfma_f32_16x16x32_bf16 v[70:73], v[174:177], v[228:231], 0
	v_mfma_f32_16x16x32_bf16 v[66:69], v[182:185], v[228:231], 0
	v_mfma_f32_16x16x32_bf16 v[118:121], v[178:181], v[208:211], v[118:121]
	v_mfma_f32_16x16x32_bf16 v[110:113], v[186:189], v[208:211], v[110:113]
	v_mfma_f32_16x16x32_bf16 v[102:105], v[178:181], v[216:219], v[102:105]
	v_mfma_f32_16x16x32_bf16 v[94:97], v[186:189], v[216:219], v[94:97]
	v_mfma_f32_16x16x32_bf16 v[86:89], v[178:181], v[224:227], v[86:89]
	v_mfma_f32_16x16x32_bf16 v[78:81], v[186:189], v[224:227], v[78:81]
	v_mfma_f32_16x16x32_bf16 v[70:73], v[178:181], v[232:235], v[70:73]
	v_mfma_f32_16x16x32_bf16 v[66:69], v[186:189], v[232:235], v[66:69]
	s_setprio 0
	s_barrier
	s_add_i32 s46, s70, s55
	v_lshl_add_u64 v[140:141], s[50:51], 0, v[0:1]
	s_mov_b32 m0, s46
	ds_read_b128 v[200:203], v145 offset:16384
	ds_read_b128 v[208:211], v145 offset:17408
	ds_read_b128 v[212:215], v145 offset:18432
	ds_read_b128 v[216:219], v145 offset:19456
	ds_read_b128 v[220:223], v145 offset:20480
	ds_read_b128 v[224:227], v145 offset:21504
	ds_read_b128 v[228:231], v145 offset:22528
	ds_read_b128 v[232:235], v145 offset:23552
	global_load_lds_dwordx4 v[140:141], off
	s_add_i32 m0, s46, 0x2000
	s_add_u32 s46, s50, 0xb0000
	v_lshl_add_u64 v[190:191], s[50:51], 0, v[130:131]
	s_addc_u32 s47, s51, 0
	s_add_i32 s70, s71, s55
	global_load_lds_dwordx4 v[190:191], off
	v_lshl_add_u64 v[236:237], s[46:47], 0, v[0:1]
	s_mov_b32 m0, s70
	v_lshl_add_u64 v[238:239], s[52:53], 0, v[132:133]
	global_load_lds_dwordx4 v[236:237], off
	v_lshl_add_u64 v[236:237], s[46:47], 0, v[130:131]
	s_add_i32 m0, s70, 0x2000
	s_nop 0
	global_load_lds_dwordx4 v[236:237], off
	v_lshl_add_u64 v[236:237], s[52:53], 0, v[134:135]
	s_mov_b32 m0, s56
	s_nop 0
	global_load_lds_dwordx4 v[236:237], off
	s_mov_b32 m0, s57
	s_nop 0
	global_load_lds_dwordx4 v[238:239], off
	s_waitcnt vmcnt(8)
	s_waitcnt lgkmcnt(0)
	s_barrier
; #define PG8_STAGEA(bufoff, gbase, voff) do { _Pragma("unroll") for (int _i = 0; _i < 2; ++_i) \
;         __builtin_amdgcn_global_load_lds((const unsigned*)((const char*)(gbase) + (voff)[_i]), (PG8_LAS unsigned*)(lds + (bufoff) + ldsw + _i * 8192), 16, 0, A_AUX); } while (0)
; #define PG8_LDA(dst, b, h) do { _Pragma("unroll") for (int m = 0; m < 4; ++m) _Pragma("unroll") for (int k = 0; k < 2; ++k) dst[m][k] = *(const PG8_LAS bf16x8*)(lds + PG8_SA(b, h) + aoff + m * 2048 + k * 1024); } while (0)
; #define PG8_LDB(dst, b, h) do { _Pragma("unroll") for (int n = 0; n < 2; ++n) _Pragma("unroll") for (int k = 0; k < 2; ++k) dst[n][k] = *(const PG8_LAS bf16x8*)(lds + PG8_SB(b, h) + boff + n * 2048 + k * 1024); } while (0)
; #define PG8_MMA(ai, bj, At, Bt) do { __builtin_amdgcn_s_setprio(1); _Pragma("unroll") for (int m = 0; m < 4; ++m) _Pragma("unroll") for (int n = 0; n < 2; ++n) _Pragma("unroll") for (int k = 0; k < 2; ++k) \
;         acc[ai][bj][m][n] = __builtin_amdgcn_mfma_f32_16x16x32_bf16(Bt[n][k], At[m][k], acc[ai][bj][m][n], 0, 0, 0); __builtin_amdgcn_s_setprio(0); } while (0)
; #define PG8_WAIT_V(n) asm volatile("s_waitcnt vmcnt(" #n ")" ::: "memory")
; #define PG8_WAIT_L(n) asm volatile("s_waitcnt lgkmcnt(" #n ")" ::: "memory")
; #define PG8_BAR __builtin_amdgcn_s_barrier()
; #define PG8_SCHED __builtin_amdgcn_sched_barrier(0)
;     ...
;             PG8_WAIT_V(8); PG8_WAIT_L(0); PG8_BAR; PG8_MMA(1, 0, At, B0); PG8_MMA(1, 1, At, B1); PG8_BAR; PG8_SCHED;
;             PG8_LDB(B0, 1, 0); PG8_LDB(B1, 1, 1); PG8_SCHED; PG8_LDA(At, 1, 0); PG8_STAGEA(PG8_SA(0, 1), a2 + hstep, voffA);
;             PG8_WAIT_V(8); PG8_WAIT_L(0); PG8_BAR; PG8_MMA(0, 0, At, B0); PG8_MMA(0, 1, At, B1); PG8_BAR; PG8_SCHED;
	s_setprio 1
	s_waitcnt lgkmcnt(0)
	v_mfma_f32_16x16x32_bf16 v[62:65], v[146:149], v[200:203], 0
	v_mfma_f32_16x16x32_bf16 v[58:61], v[154:157], v[200:203], 0
	v_mfma_f32_16x16x32_bf16 v[50:53], v[146:149], v[212:215], 0
	v_mfma_f32_16x16x32_bf16 v[42:45], v[154:157], v[212:215], 0
	v_mfma_f32_16x16x32_bf16 v[34:37], v[146:149], v[220:223], 0
	v_mfma_f32_16x16x32_bf16 v[26:29], v[154:157], v[220:223], 0
	v_mfma_f32_16x16x32_bf16 v[18:21], v[146:149], v[228:231], 0
	v_mfma_f32_16x16x32_bf16 v[10:13], v[154:157], v[228:231], 0
	v_mfma_f32_16x16x32_bf16 v[62:65], v[150:153], v[208:211], v[62:65]
	v_mfma_f32_16x16x32_bf16 v[58:61], v[158:161], v[208:211], v[58:61]
	v_mfma_f32_16x16x32_bf16 v[50:53], v[150:153], v[216:219], v[50:53]
	v_mfma_f32_16x16x32_bf16 v[42:45], v[158:161], v[216:219], v[42:45]
	v_mfma_f32_16x16x32_bf16 v[34:37], v[150:153], v[224:227], v[34:37]
	v_mfma_f32_16x16x32_bf16 v[26:29], v[158:161], v[224:227], v[26:29]
	v_mfma_f32_16x16x32_bf16 v[18:21], v[150:153], v[232:235], v[18:21]
	v_mfma_f32_16x16x32_bf16 v[10:13], v[158:161], v[232:235], v[10:13]
	s_setprio 0
	s_setprio 1
	v_mfma_f32_16x16x32_bf16 v[54:57], v[174:177], v[200:203], 0
	v_mfma_f32_16x16x32_bf16 v[46:49], v[182:185], v[200:203], 0
	v_mfma_f32_16x16x32_bf16 v[38:41], v[174:177], v[212:215], 0
	v_mfma_f32_16x16x32_bf16 v[30:33], v[182:185], v[212:215], 0
	v_mfma_f32_16x16x32_bf16 v[22:25], v[174:177], v[220:223], 0
	v_mfma_f32_16x16x32_bf16 v[14:17], v[182:185], v[220:223], 0
	v_mfma_f32_16x16x32_bf16 v[6:9], v[174:177], v[228:231], 0
	v_mfma_f32_16x16x32_bf16 v[2:5], v[182:185], v[228:231], 0
	v_mfma_f32_16x16x32_bf16 v[54:57], v[178:181], v[208:211], v[54:57]
	v_mfma_f32_16x16x32_bf16 v[46:49], v[186:189], v[208:211], v[46:49]
	v_mfma_f32_16x16x32_bf16 v[38:41], v[178:181], v[216:219], v[38:41]
	v_mfma_f32_16x16x32_bf16 v[30:33], v[186:189], v[216:219], v[30:33]
	v_mfma_f32_16x16x32_bf16 v[22:25], v[178:181], v[224:227], v[22:25]
	v_mfma_f32_16x16x32_bf16 v[14:17], v[186:189], v[224:227], v[14:17]
	v_mfma_f32_16x16x32_bf16 v[6:9], v[178:181], v[232:235], v[6:9]
	v_mfma_f32_16x16x32_bf16 v[2:5], v[186:189], v[232:235], v[2:5]
	s_setprio 0
	s_barrier
	s_add_i32 s70, 0, 0x18000
	s_add_i32 s71, 0, 0x1c000
	v_add_u32_e32 v158, s70, v143
	v_add_u32_e32 v186, s71, v143
	ds_read_b128 v[146:149], v158
	ds_read_b128 v[150:153], v158 offset:1024
	ds_read_b128 v[154:157], v158 offset:2048
	ds_read_b128 v[158:161], v158 offset:3072
	ds_read_b128 v[174:177], v186
	ds_read_b128 v[178:181], v186 offset:1024
	ds_read_b128 v[182:185], v186 offset:2048
	ds_read_b128 v[186:189], v186 offset:3072
	s_add_u32 s46, s52, 0xb0000
	s_addc_u32 s47, s53, 0
	s_mov_b32 m0, s58
	v_lshl_add_u64 v[240:241], s[46:47], 0, v[134:135]
	ds_read_b128 v[200:203], v145 offset:32768
	ds_read_b128 v[208:211], v145 offset:33792
	ds_read_b128 v[212:215], v145 offset:34816
	ds_read_b128 v[216:219], v145 offset:35840
	ds_read_b128 v[220:223], v145 offset:36864
	ds_read_b128 v[224:227], v145 offset:37888
	ds_read_b128 v[228:231], v145 offset:38912
	ds_read_b128 v[232:235], v145 offset:39936
	global_load_lds_dwordx4 v[240:241], off
	v_lshl_add_u64 v[240:241], s[46:47], 0, v[132:133]
	s_mov_b32 m0, s59
	s_nop 0
	global_load_lds_dwordx4 v[240:241], off
	s_waitcnt vmcnt(8)
	s_waitcnt lgkmcnt(0)
	s_barrier
	s_setprio 1
	s_waitcnt lgkmcnt(0)
	v_mfma_f32_16x16x32_bf16 v[126:129], v[146:149], v[200:203], v[126:129]
	v_mfma_f32_16x16x32_bf16 v[122:125], v[154:157], v[200:203], v[122:125]
	v_mfma_f32_16x16x32_bf16 v[114:117], v[146:149], v[212:215], v[114:117]
	v_mfma_f32_16x16x32_bf16 v[106:109], v[154:157], v[212:215], v[106:109]
	v_mfma_f32_16x16x32_bf16 v[98:101], v[146:149], v[220:223], v[98:101]
	v_mfma_f32_16x16x32_bf16 v[90:93], v[154:157], v[220:223], v[90:93]
	v_mfma_f32_16x16x32_bf16 v[82:85], v[146:149], v[228:231], v[82:85]
	v_mfma_f32_16x16x32_bf16 v[74:77], v[154:157], v[228:231], v[74:77]
	v_mfma_f32_16x16x32_bf16 v[126:129], v[150:153], v[208:211], v[126:129]
	v_mfma_f32_16x16x32_bf16 v[122:125], v[158:161], v[208:211], v[122:125]
	v_mfma_f32_16x16x32_bf16 v[114:117], v[150:153], v[216:219], v[114:117]
	v_mfma_f32_16x16x32_bf16 v[106:109], v[158:161], v[216:219], v[106:109]
	v_mfma_f32_16x16x32_bf16 v[98:101], v[150:153], v[224:227], v[98:101]
	v_mfma_f32_16x16x32_bf16 v[90:93], v[158:161], v[224:227], v[90:93]
	v_mfma_f32_16x16x32_bf16 v[82:85], v[150:153], v[232:235], v[82:85]
	v_mfma_f32_16x16x32_bf16 v[74:77], v[158:161], v[232:235], v[74:77]
	s_setprio 0
	s_setprio 1
	v_mfma_f32_16x16x32_bf16 v[118:121], v[174:177], v[200:203], v[118:121]
	v_mfma_f32_16x16x32_bf16 v[110:113], v[182:185], v[200:203], v[110:113]
	v_mfma_f32_16x16x32_bf16 v[102:105], v[174:177], v[212:215], v[102:105]
	v_mfma_f32_16x16x32_bf16 v[94:97], v[182:185], v[212:215], v[94:97]
	v_mfma_f32_16x16x32_bf16 v[86:89], v[174:177], v[220:223], v[86:89]
	v_mfma_f32_16x16x32_bf16 v[78:81], v[182:185], v[220:223], v[78:81]
	v_mfma_f32_16x16x32_bf16 v[70:73], v[174:177], v[228:231], v[70:73]
	v_mfma_f32_16x16x32_bf16 v[66:69], v[182:185], v[228:231], v[66:69]
	v_mfma_f32_16x16x32_bf16 v[118:121], v[178:181], v[208:211], v[118:121]
	v_mfma_f32_16x16x32_bf16 v[110:113], v[186:189], v[208:211], v[110:113]
	v_mfma_f32_16x16x32_bf16 v[102:105], v[178:181], v[216:219], v[102:105]
	v_mfma_f32_16x16x32_bf16 v[94:97], v[186:189], v[216:219], v[94:97]
	v_mfma_f32_16x16x32_bf16 v[86:89], v[178:181], v[224:227], v[86:89]
	v_mfma_f32_16x16x32_bf16 v[78:81], v[186:189], v[224:227], v[78:81]
	v_mfma_f32_16x16x32_bf16 v[70:73], v[178:181], v[232:235], v[70:73]
	v_mfma_f32_16x16x32_bf16 v[66:69], v[186:189], v[232:235], v[66:69]
	s_setprio 0
	s_barrier
; #define PG8_STAGE(bufoff, gbase, voff) do { _Pragma("unroll") for (int _i = 0; _i < 2; ++_i) \
;         __builtin_amdgcn_global_load_lds((const unsigned*)((const char*)(gbase) + (voff)[_i]), (PG8_LAS unsigned*)(lds + (bufoff) + ldsw + _i * 8192), 16, 0, 0); } while (0)
; #define PG8_STAGEA(bufoff, gbase, voff) do { _Pragma("unroll") for (int _i = 0; _i < 2; ++_i) \
;         __builtin_amdgcn_global_load_lds((const unsigned*)((const char*)(gbase) + (voff)[_i]), (PG8_LAS unsigned*)(lds + (bufoff) + ldsw + _i * 8192), 16, 0, A_AUX); } while (0)
; #define PG8_LDA(dst, b, h) do { _Pragma("unroll") for (int m = 0; m < 4; ++m) _Pragma("unroll") for (int k = 0; k < 2; ++k) dst[m][k] = *(const PG8_LAS bf16x8*)(lds + PG8_SA(b, h) + aoff + m * 2048 + k * 1024); } while (0)
; #define PG8_MMA(ai, bj, At, Bt) do { __builtin_amdgcn_s_setprio(1); _Pragma("unroll") for (int m = 0; m < 4; ++m) _Pragma("unroll") for (int n = 0; n < 2; ++n) _Pragma("unroll") for (int k = 0; k < 2; ++k) \
;         acc[ai][bj][m][n] = __builtin_amdgcn_mfma_f32_16x16x32_bf16(Bt[n][k], At[m][k], acc[ai][bj][m][n], 0, 0, 0); __builtin_amdgcn_s_setprio(0); } while (0)
; #define PG8_WAIT_V(n) asm volatile("s_waitcnt vmcnt(" #n ")" ::: "memory")
; #define PG8_WAIT_L(n) asm volatile("s_waitcnt lgkmcnt(" #n ")" ::: "memory")
; #define PG8_BAR __builtin_amdgcn_s_barrier()
; #define PG8_SCHED __builtin_amdgcn_sched_barrier(0)
;     ...
;             PG8_LDA(At, 1, 1); PG8_STAGE(PG8_SB(1, 0), b3, voffB); PG8_STAGE(PG8_SB(1, 1), b3 + hstep, voffB); PG8_STAGEA(PG8_SA(1, 0), a3, voffA);
;             PG8_WAIT_V(8); PG8_WAIT_L(0); PG8_BAR; PG8_MMA(1, 0, At, B0); PG8_MMA(1, 1, At, B1); PG8_BAR; PG8_SCHED;
	s_add_i32 s46, s70, s55
	v_lshl_add_u64 v[140:141], v[140:141], 0, s[8:9]
	s_mov_b32 m0, s46
	ds_read_b128 v[200:203], v145 offset:49152
	ds_read_b128 v[208:211], v145 offset:50176
	ds_read_b128 v[212:215], v145 offset:51200
	ds_read_b128 v[216:219], v145 offset:52224
	ds_read_b128 v[220:223], v145 offset:53248
	ds_read_b128 v[224:227], v145 offset:54272
	ds_read_b128 v[228:231], v145 offset:55296
	ds_read_b128 v[232:235], v145 offset:56320
	global_load_lds_dwordx4 v[140:141], off
	s_add_i32 m0, s46, 0x2000
	s_add_u32 s46, s50, 0xb0080
	v_lshl_add_u64 v[140:141], v[190:191], 0, s[8:9]
	s_addc_u32 s47, s51, 0
	s_add_i32 s50, s71, s55
	global_load_lds_dwordx4 v[140:141], off
	v_lshl_add_u64 v[140:141], s[46:47], 0, v[0:1]
	s_mov_b32 m0, s50
	s_nop 0
	global_load_lds_dwordx4 v[140:141], off
	v_lshl_add_u64 v[140:141], s[46:47], 0, v[130:131]
	s_add_i32 m0, s50, 0x2000
	s_nop 0
	global_load_lds_dwordx4 v[140:141], off
	v_lshl_add_u64 v[140:141], v[236:237], 0, s[8:9]
	s_mov_b32 m0, s60
	s_nop 0
	global_load_lds_dwordx4 v[140:141], off
	v_lshl_add_u64 v[140:141], v[238:239], 0, s[8:9]
	s_mov_b32 m0, s61
	s_nop 0
	global_load_lds_dwordx4 v[140:141], off
	s_waitcnt vmcnt(8)
	s_waitcnt lgkmcnt(0)
	s_barrier
	s_setprio 1
	s_waitcnt lgkmcnt(0)
	v_mfma_f32_16x16x32_bf16 v[62:65], v[146:149], v[200:203], v[62:65]
	v_mfma_f32_16x16x32_bf16 v[58:61], v[154:157], v[200:203], v[58:61]
	v_mfma_f32_16x16x32_bf16 v[50:53], v[146:149], v[212:215], v[50:53]
	v_mfma_f32_16x16x32_bf16 v[42:45], v[154:157], v[212:215], v[42:45]
	v_mfma_f32_16x16x32_bf16 v[34:37], v[146:149], v[220:223], v[34:37]
	v_mfma_f32_16x16x32_bf16 v[26:29], v[154:157], v[220:223], v[26:29]
	v_mfma_f32_16x16x32_bf16 v[18:21], v[146:149], v[228:231], v[18:21]
	v_mfma_f32_16x16x32_bf16 v[10:13], v[154:157], v[228:231], v[10:13]
	v_mfma_f32_16x16x32_bf16 v[62:65], v[150:153], v[208:211], v[62:65]
	v_mfma_f32_16x16x32_bf16 v[58:61], v[158:161], v[208:211], v[58:61]
	v_mfma_f32_16x16x32_bf16 v[50:53], v[150:153], v[216:219], v[50:53]
	v_mfma_f32_16x16x32_bf16 v[42:45], v[158:161], v[216:219], v[42:45]
	v_mfma_f32_16x16x32_bf16 v[34:37], v[150:153], v[224:227], v[34:37]
	v_mfma_f32_16x16x32_bf16 v[26:29], v[158:161], v[224:227], v[26:29]
	v_mfma_f32_16x16x32_bf16 v[18:21], v[150:153], v[232:235], v[18:21]
	v_mfma_f32_16x16x32_bf16 v[10:13], v[158:161], v[232:235], v[10:13]
	s_setprio 0
	s_setprio 1
	v_mfma_f32_16x16x32_bf16 v[54:57], v[174:177], v[200:203], v[54:57]
	v_mfma_f32_16x16x32_bf16 v[46:49], v[182:185], v[200:203], v[46:49]
	v_mfma_f32_16x16x32_bf16 v[38:41], v[174:177], v[212:215], v[38:41]
	v_mfma_f32_16x16x32_bf16 v[30:33], v[182:185], v[212:215], v[30:33]
	v_mfma_f32_16x16x32_bf16 v[22:25], v[174:177], v[220:223], v[22:25]
	v_mfma_f32_16x16x32_bf16 v[14:17], v[182:185], v[220:223], v[14:17]
	v_mfma_f32_16x16x32_bf16 v[6:9], v[174:177], v[228:231], v[6:9]
	v_mfma_f32_16x16x32_bf16 v[2:5], v[182:185], v[228:231], v[2:5]
	v_mfma_f32_16x16x32_bf16 v[54:57], v[178:181], v[208:211], v[54:57]
	v_mfma_f32_16x16x32_bf16 v[46:49], v[186:189], v[208:211], v[46:49]
	v_mfma_f32_16x16x32_bf16 v[38:41], v[178:181], v[216:219], v[38:41]
	v_mfma_f32_16x16x32_bf16 v[30:33], v[186:189], v[216:219], v[30:33]
	v_mfma_f32_16x16x32_bf16 v[22:25], v[178:181], v[224:227], v[22:25]
	v_mfma_f32_16x16x32_bf16 v[14:17], v[186:189], v[224:227], v[14:17]
	v_mfma_f32_16x16x32_bf16 v[6:9], v[178:181], v[232:235], v[6:9]
	v_mfma_f32_16x16x32_bf16 v[2:5], v[186:189], v[232:235], v[2:5]
	s_setprio 0
	s_barrier
	s_add_i32 s73, s73, 2
	s_add_u32 s16, s16, 0x100
	s_addc_u32 s17, s17, 0
	s_cmp_gt_u32 s73, 41
	s_mov_b64 s[46:47], s[48:49]
	.p2align 6
